# MLA KV loop unrolled x6 (K parity and V ring slot as immediates; no per-tile ring bookkeeping), rest as previous
# speedup vs baseline: 1.0044x; 1.0044x over previous
; template <int DQK, int DV, int RH, bool NEGM> ...
;     ...
;     AT_GLOAD(0); AT_LSTORE(0, 0); __syncthreads();
;     int vs_prev = 2, vs_cur = 0, vs_next = 1;
;     if (!grpB) {
;         for (int t = 0; t < NT; ++t) {
;             const int kb = t & 1;
;             if (t + 1 < NT) AT_GLOAD(t + 1);
.LBB0_871:
	s_or_b64 exec, exec, s[44:45]
	v_mul_lo_u32 v5, v8, s57
	v_and_b32_e32 v241, 6, v132
	v_lshlrev_b32_e32 v241, 4, v241
	v_and_b32_e32 v242, 1, v132
	v_lshl_or_b32 v241, v242, 3, v241
	v_add3_u32 v166, 0, v5, v241
	v_add_u32_e32 v5, 0x6800, v166
	v_add_u32_e32 v243, 0x6800, v166
	v_add_u32_e32 v246, 0x8c00, v166
	v_add_u32_e32 v247, 0xb000, v166
	s_waitcnt vmcnt(0)
	ds_write2_b64 v5, v[0:1], v[2:3] offset1:2
	s_waitcnt lgkmcnt(0)
	s_barrier
	s_and_saveexec_b64 s[44:45], s[6:7]
	s_cbranch_execz .LBB0_873
	v_add_u32_e32 v0, v136, v135
	v_mul_lo_u32 v1, v0, 12
	v_sub_u32_e32 v2, v133, v1
	v_add_u32_e32 v3, 64, v0
	v_mov_b64_e32 v[0:1], s[42:43]
	v_lshlrev_b32_e32 v2, 3, v2
	v_mad_i64_i32 v[0:1], s[62:63], v3, s51, v[0:1]
	v_ashrrev_i32_e32 v3, 31, v2
	v_lshl_add_u64 v[0:1], v[2:3], 1, v[0:1]
	global_load_dwordx4 v[104:107], v[0:1], off

.Lmla_loop:
	global_load_dwordx4 v[104:107], v154, s[98:99]
	s_mov_b64 exec, s[8:9]
	global_load_dwordx4 v[108:111], v156, s[98:99]
	s_mov_b64 exec, -1
	global_load_dwordx4 v[112:115], v158, s[100:101]
	s_add_u32 s98, s98, 0x18000
	s_addc_u32 s99, s99, 0
	s_add_u32 s100, s100, 0x80
	s_addc_u32 s101, s101, 0
	ds_read_b128 v[48:51], v169 offset:13312
	ds_read_b128 v[52:55], v169 offset:13344
	ds_read_b128 v[116:119], v169 offset:19968
	ds_read_b128 v[120:123], v169 offset:20000
	s_waitcnt lgkmcnt(3)
	v_mfma_f32_32x32x16_bf16 v[64:79], v[48:51], v[100:103], v[32:47]
	ds_read_b128 v[124:127], v169 offset:13376
	ds_read_b128 v[128:131], v169 offset:13408
	ds_read_b128 v[132:135], v169 offset:20032
	ds_read_b128 v[136:139], v169 offset:20064
	s_waitcnt lgkmcnt(4)
	v_mfma_f32_32x32x16_bf16 v[64:79], v[52:55], v[96:99], v[64:79]
	v_mfma_f32_32x32x16_bf16 v[48:63], v[116:119], v[100:103], v[32:47]
	v_mfma_f32_32x32x16_bf16 v[48:63], v[120:123], v[96:99], v[48:63]
	s_waitcnt lgkmcnt(1)
	v_mfma_f32_32x32x16_bf16 v[64:79], v[124:127], v[92:95], v[64:79]
	v_mfma_f32_32x32x16_bf16 v[48:63], v[132:135], v[92:95], v[48:63]
	v_mfma_f32_32x32x16_bf16 v[64:79], v[128:131], v[88:91], v[64:79]
	ds_read_b128 v[116:119], v169 offset:13440
	ds_read_b128 v[120:123], v169 offset:13472
	ds_read_b128 v[128:131], v169 offset:20096
	ds_read_b128 v[176:179], v169 offset:20128
	s_waitcnt lgkmcnt(3)
	v_mfma_f32_32x32x16_bf16 v[48:63], v[136:139], v[88:91], v[48:63]
	v_mfma_f32_32x32x16_bf16 v[64:79], v[116:119], v[84:87], v[64:79]
	ds_read_b128 v[136:139], v170 offset:35840
	ds_read_b128 v[124:127], v170 offset:35872
	s_waitcnt lgkmcnt(3)
	v_mfma_f32_32x32x16_bf16 v[48:63], v[128:131], v[84:87], v[48:63]
	v_mfma_f32_32x32x16_bf16 v[64:79], v[120:123], v[80:83], v[64:79]
	ds_read_b128 v[132:135], v170 offset:35904
	ds_read_b128 v[120:123], v170 offset:35936
	ds_read_b128 v[144:147], v170 offset:40448
	ds_read_b128 v[140:143], v170 offset:40480
	ds_read_b128 v[128:131], v170 offset:40512
	ds_read_b128 v[116:119], v170 offset:40544
	s_waitcnt lgkmcnt(8)
	v_mfma_f32_32x32x16_bf16 v[48:63], v[176:179], v[80:83], v[48:63]
	s_add_i32 s43, s43, 1
	s_nop 10
	v_max_f32_e32 v148, v64, v48
	v_max_f32_e32 v160, v65, v49
	v_max_f32_e32 v161, v67, v51
	v_max3_f32 v176, v66, v50, v70
	v_max3_f32 v161, v161, v71, v55
	v_max3_f32 v148, v148, v68, v52
	v_max3_f32 v160, v160, v69, v53
	v_max3_f32 v176, v176, v54, v74
	v_max3_f32 v161, v161, v75, v59
	v_max3_f32 v148, v148, v72, v56
	v_max3_f32 v160, v160, v73, v57
	v_max3_f32 v176, v176, v58, v78
	v_max3_f32 v161, v161, v79, v63
	v_max3_f32 v148, v148, v76, v60
	v_max3_f32 v160, v160, v77, v61
	v_max3_f32 v161, v176, v62, v161
	v_max3_f32 v148, v148, v160, v161
	v_cmp_lt_f32_e32 vcc, s59, v148
	s_cbranch_vccz .Lmla_norescale_1
	v_mov_b32_e32 v160, v148
	s_nop 1
	v_permlane32_swap_b32_e32 v148, v160
	v_max_f32_e32 v148, v148, v160
	v_max_f32_e32 v32, v148, v148
	v_max_f32_e32 v148, 0, v32
	v_exp_f32_e64 v160, -v148
	v_add_f32_e32 v168, v168, v148
	v_xor_b32_e32 v32, 0x80000000, v168
	v_mov_b32_e32 v33, v32
	v_mov_b32_e32 v34, v32
	v_mov_b32_e32 v35, v32
	v_mov_b32_e32 v36, v32
	v_mov_b32_e32 v37, v32
	v_mov_b32_e32 v38, v32
	v_mov_b32_e32 v39, v32
	v_mov_b32_e32 v40, v32
	v_mov_b32_e32 v41, v32
	v_mov_b32_e32 v42, v32
	v_mov_b32_e32 v43, v32
	v_mov_b32_e32 v44, v32
	v_mov_b32_e32 v45, v32
	v_mov_b32_e32 v46, v32
	v_mov_b32_e32 v47, v32
	v_pk_add_f32 v[64:65], v[64:65], v[148:149] op_sel_hi:[1,0] neg_lo:[0,1] neg_hi:[0,1]
	v_pk_add_f32 v[48:49], v[48:49], v[148:149] op_sel_hi:[1,0] neg_lo:[0,1] neg_hi:[0,1]
	v_pk_add_f32 v[66:67], v[66:67], v[148:149] op_sel_hi:[1,0] neg_lo:[0,1] neg_hi:[0,1]
	v_pk_add_f32 v[50:51], v[50:51], v[148:149] op_sel_hi:[1,0] neg_lo:[0,1] neg_hi:[0,1]
	v_pk_add_f32 v[68:69], v[68:69], v[148:149] op_sel_hi:[1,0] neg_lo:[0,1] neg_hi:[0,1]
	v_pk_add_f32 v[52:53], v[52:53], v[148:149] op_sel_hi:[1,0] neg_lo:[0,1] neg_hi:[0,1]
	v_pk_add_f32 v[70:71], v[70:71], v[148:149] op_sel_hi:[1,0] neg_lo:[0,1] neg_hi:[0,1]
	v_pk_add_f32 v[54:55], v[54:55], v[148:149] op_sel_hi:[1,0] neg_lo:[0,1] neg_hi:[0,1]
	v_pk_add_f32 v[72:73], v[72:73], v[148:149] op_sel_hi:[1,0] neg_lo:[0,1] neg_hi:[0,1]
	v_pk_add_f32 v[56:57], v[56:57], v[148:149] op_sel_hi:[1,0] neg_lo:[0,1] neg_hi:[0,1]
	v_pk_add_f32 v[74:75], v[74:75], v[148:149] op_sel_hi:[1,0] neg_lo:[0,1] neg_hi:[0,1]
	v_pk_add_f32 v[58:59], v[58:59], v[148:149] op_sel_hi:[1,0] neg_lo:[0,1] neg_hi:[0,1]
	v_pk_add_f32 v[76:77], v[76:77], v[148:149] op_sel_hi:[1,0] neg_lo:[0,1] neg_hi:[0,1]
	v_pk_add_f32 v[60:61], v[60:61], v[148:149] op_sel_hi:[1,0] neg_lo:[0,1] neg_hi:[0,1]
	v_pk_add_f32 v[78:79], v[78:79], v[148:149] op_sel_hi:[1,0] neg_lo:[0,1] neg_hi:[0,1]
	v_pk_add_f32 v[62:63], v[62:63], v[148:149] op_sel_hi:[1,0] neg_lo:[0,1] neg_hi:[0,1]
	v_pk_mul_f32 v[30:31], v[30:31], v[160:161] op_sel_hi:[1,0]
	v_pk_mul_f32 v[28:29], v[28:29], v[160:161] op_sel_hi:[1,0]
	v_pk_mul_f32 v[26:27], v[26:27], v[160:161] op_sel_hi:[1,0]
	v_pk_mul_f32 v[24:25], v[24:25], v[160:161] op_sel_hi:[1,0]
	v_pk_mul_f32 v[22:23], v[22:23], v[160:161] op_sel_hi:[1,0]
	v_pk_mul_f32 v[20:21], v[20:21], v[160:161] op_sel_hi:[1,0]
	v_pk_mul_f32 v[18:19], v[18:19], v[160:161] op_sel_hi:[1,0]
	v_pk_mul_f32 v[16:17], v[16:17], v[160:161] op_sel_hi:[1,0]
	v_pk_mul_f32 v[14:15], v[14:15], v[160:161] op_sel_hi:[1,0]
	v_pk_mul_f32 v[12:13], v[12:13], v[160:161] op_sel_hi:[1,0]
	v_pk_mul_f32 v[10:11], v[10:11], v[160:161] op_sel_hi:[1,0]
	v_pk_mul_f32 v[8:9], v[8:9], v[160:161] op_sel_hi:[1,0]
	v_pk_mul_f32 v[6:7], v[6:7], v[160:161] op_sel_hi:[1,0]
	v_pk_mul_f32 v[4:5], v[4:5], v[160:161] op_sel_hi:[1,0]
	v_pk_mul_f32 v[2:3], v[2:3], v[160:161] op_sel_hi:[1,0]
	v_pk_mul_f32 v[0:1], v[0:1], v[160:161] op_sel_hi:[1,0]
	v_pk_mul_f32 v[152:153], v[152:153], v[160:161] op_sel_hi:[1,0]
	v_pk_mul_f32 v[150:151], v[150:151], v[160:161] op_sel_hi:[1,0]
; #define AT_QK_LD0(kb_) do { if constexpr (NEGM) { const LAS unsigned char* kbp_ = Kl + (kb_) * KBUF + r32 * KROWB + hi * 16; AT_KLD2(0); __builtin_amdgcn_sched_barrier(0); } } while (0)
; template <int DQK, int DV, int RH, bool NEGM> ...
;     ...
;     const int NT = nkv / 64;
;     AT_GLOAD(0); AT_LSTORE(0, 0); __syncthreads();
;     int vs_prev = 2, vs_cur = 0, vs_next = 1;
;     if (!grpB) {
;         for (int t = 0; t < NT; ++t) {
;             const int kb = t & 1;
;             if (t + 1 < NT) AT_GLOAD(t + 1);
;             f32x16 p[RH][2];
;             AT_QK_LD0(kb); AT_QK(kb); AT_VLOAD(vs_cur); AT_SOFTMAX(); AT_PV(vs_cur);
;             if (t + 1 < NT) AT_LSTORE(kb ^ 1, vs_next);
;             __syncthreads();
;             vs_prev = vs_cur; vs_cur = vs_next; vs_next = (vs_next == 2) ? 0 : vs_next + 1;
.Lmla_norescale_1:
	v_exp_f32_e32 v160, v64
	v_exp_f32_e32 v161, v65
	v_exp_f32_e32 v64, v66
	v_exp_f32_e32 v65, v67
	v_exp_f32_e32 v68, v68
	v_exp_f32_e32 v69, v69
	v_exp_f32_e32 v66, v70
	v_exp_f32_e32 v67, v71
	v_cvt_pk_bf16_f32 v176, v160, v161
	v_cvt_pk_bf16_f32 v177, v64, v65
	v_cvt_pk_bf16_f32 v178, v68, v69
	v_cvt_pk_bf16_f32 v179, v66, v67
	v_exp_f32_e32 v70, v74
	v_exp_f32_e32 v71, v75
	s_waitcnt lgkmcnt(0)
	v_mfma_f32_32x32x16_bf16 v[16:31], v[136:139], v[176:179], v[16:31]
	v_exp_f32_e32 v136, v72
	v_exp_f32_e32 v137, v73
	v_exp_f32_e32 v74, v76
	v_exp_f32_e32 v75, v77
	v_exp_f32_e32 v72, v78
	v_exp_f32_e32 v73, v79
	v_exp_f32_e32 v76, v48
	v_mfma_f32_32x32x16_bf16 v[0:15], v[144:147], v[176:179], v[0:15]
	v_cvt_pk_bf16_f32 v144, v136, v137
	v_cvt_pk_bf16_f32 v145, v70, v71
	v_cvt_pk_bf16_f32 v146, v74, v75
	v_cvt_pk_bf16_f32 v147, v72, v73
	v_exp_f32_e32 v77, v49
	v_exp_f32_e32 v48, v50
	v_exp_f32_e32 v49, v51
	v_mfma_f32_32x32x16_bf16 v[16:31], v[124:127], v[144:147], v[16:31]
	v_exp_f32_e32 v52, v52
	v_exp_f32_e32 v53, v53
	v_exp_f32_e32 v50, v54
	v_exp_f32_e32 v51, v55
	v_cvt_pk_bf16_f32 v124, v76, v77
	v_cvt_pk_bf16_f32 v125, v48, v49
	v_cvt_pk_bf16_f32 v126, v52, v53
	v_mfma_f32_32x32x16_bf16 v[0:15], v[140:143], v[144:147], v[0:15]
	v_cvt_pk_bf16_f32 v127, v50, v51
	v_exp_f32_e32 v78, v56
	v_exp_f32_e32 v79, v57
	v_exp_f32_e32 v54, v58
	v_exp_f32_e32 v55, v59
	v_exp_f32_e32 v58, v60
	v_exp_f32_e32 v59, v61
	v_mfma_f32_32x32x16_bf16 v[16:31], v[132:135], v[124:127], v[16:31]
	v_exp_f32_e32 v56, v62
	v_exp_f32_e32 v57, v63
	v_cvt_pk_bf16_f32 v60, v78, v79
	v_cvt_pk_bf16_f32 v61, v54, v55
	v_cvt_pk_bf16_f32 v62, v58, v59
	v_cvt_pk_bf16_f32 v63, v56, v57
	v_mfma_f32_32x32x16_bf16 v[0:15], v[128:131], v[124:127], v[0:15]
	v_mfma_f32_32x32x16_bf16 v[16:31], v[120:123], v[60:63], v[16:31]
	v_mfma_f32_32x32x16_bf16 v[0:15], v[116:119], v[60:63], v[0:15]
	s_waitcnt vmcnt(1)
	ds_write_b128 v244, v[104:107]
	s_mov_b64 exec, s[8:9]
	ds_write_b128 v245, v[108:111]
	s_mov_b64 exec, -1
	s_waitcnt vmcnt(0)
	ds_write2_b64 v247, v[112:113], v[114:115] offset1:2
	v_pk_add_f32 v[48:49], v[64:65], v[48:49]
	v_pk_add_f32 v[60:61], v[160:161], v[76:77]
	v_pk_add_f32 v[48:49], v[152:153], v[48:49]
	v_pk_add_f32 v[50:51], v[66:67], v[50:51]
	v_pk_add_f32 v[60:61], v[150:151], v[60:61]
	v_pk_add_f32 v[52:53], v[68:69], v[52:53]
	v_pk_add_f32 v[48:49], v[50:51], v[48:49]
	v_pk_add_f32 v[50:51], v[70:71], v[54:55]
	v_pk_add_f32 v[52:53], v[52:53], v[60:61]
	v_pk_add_f32 v[60:61], v[136:137], v[78:79]
	v_pk_add_f32 v[48:49], v[50:51], v[48:49]
	v_pk_add_f32 v[50:51], v[72:73], v[56:57]
	v_pk_add_f32 v[52:53], v[60:61], v[52:53]
	v_pk_add_f32 v[58:59], v[74:75], v[58:59]
	v_pk_add_f32 v[152:153], v[50:51], v[48:49]
	v_pk_add_f32 v[150:151], v[58:59], v[52:53]
	s_waitcnt lgkmcnt(0)
	s_barrier
	global_load_dwordx4 v[104:107], v154, s[98:99]
	s_mov_b64 exec, s[8:9]
	global_load_dwordx4 v[108:111], v156, s[98:99]
	s_mov_b64 exec, -1
	global_load_dwordx4 v[112:115], v158, s[100:101]
	s_add_u32 s98, s98, 0x18000
	s_addc_u32 s99, s99, 0
	s_add_u32 s100, s100, 0x80
	s_addc_u32 s101, s101, 0
	ds_read_b128 v[48:51], v169
	ds_read_b128 v[52:55], v169 offset:32
	ds_read_b128 v[116:119], v169 offset:6656
	ds_read_b128 v[120:123], v169 offset:6688
	s_waitcnt lgkmcnt(3)
	v_mfma_f32_32x32x16_bf16 v[64:79], v[48:51], v[100:103], v[32:47]
	ds_read_b128 v[124:127], v169 offset:64
	ds_read_b128 v[128:131], v169 offset:96
	ds_read_b128 v[132:135], v169 offset:6720
	ds_read_b128 v[136:139], v169 offset:6752
	s_waitcnt lgkmcnt(4)
	v_mfma_f32_32x32x16_bf16 v[64:79], v[52:55], v[96:99], v[64:79]
	v_mfma_f32_32x32x16_bf16 v[48:63], v[116:119], v[100:103], v[32:47]
	v_mfma_f32_32x32x16_bf16 v[48:63], v[120:123], v[96:99], v[48:63]
	s_waitcnt lgkmcnt(1)
	v_mfma_f32_32x32x16_bf16 v[64:79], v[124:127], v[92:95], v[64:79]
	v_mfma_f32_32x32x16_bf16 v[48:63], v[132:135], v[92:95], v[48:63]
	v_mfma_f32_32x32x16_bf16 v[64:79], v[128:131], v[88:91], v[64:79]
	ds_read_b128 v[116:119], v169 offset:128
	ds_read_b128 v[120:123], v169 offset:160
	ds_read_b128 v[128:131], v169 offset:6784
	ds_read_b128 v[176:179], v169 offset:6816
	s_waitcnt lgkmcnt(3)
	v_mfma_f32_32x32x16_bf16 v[48:63], v[136:139], v[88:91], v[48:63]
	v_mfma_f32_32x32x16_bf16 v[64:79], v[116:119], v[84:87], v[64:79]
	ds_read_b128 v[136:139], v170 offset:45056
	ds_read_b128 v[124:127], v170 offset:45088
	s_waitcnt lgkmcnt(3)
	v_mfma_f32_32x32x16_bf16 v[48:63], v[128:131], v[84:87], v[48:63]
	v_mfma_f32_32x32x16_bf16 v[64:79], v[120:123], v[80:83], v[64:79]
	ds_read_b128 v[132:135], v170 offset:45120
	ds_read_b128 v[120:123], v170 offset:45152
	ds_read_b128 v[144:147], v170 offset:49664
	ds_read_b128 v[140:143], v170 offset:49696
	ds_read_b128 v[128:131], v170 offset:49728
	ds_read_b128 v[116:119], v170 offset:49760
	s_waitcnt lgkmcnt(8)
	v_mfma_f32_32x32x16_bf16 v[48:63], v[176:179], v[80:83], v[48:63]
	s_add_i32 s43, s43, 1
	s_nop 10
	v_max_f32_e32 v148, v64, v48
	v_max_f32_e32 v160, v65, v49
	v_max_f32_e32 v161, v67, v51
	v_max3_f32 v176, v66, v50, v70
	v_max3_f32 v161, v161, v71, v55
	v_max3_f32 v148, v148, v68, v52
	v_max3_f32 v160, v160, v69, v53
	v_max3_f32 v176, v176, v54, v74
	v_max3_f32 v161, v161, v75, v59
	v_max3_f32 v148, v148, v72, v56
	v_max3_f32 v160, v160, v73, v57
	v_max3_f32 v176, v176, v58, v78
	v_max3_f32 v161, v161, v79, v63
	v_max3_f32 v148, v148, v76, v60
	v_max3_f32 v160, v160, v77, v61
	v_max3_f32 v161, v176, v62, v161
	v_max3_f32 v148, v148, v160, v161
	v_cmp_lt_f32_e32 vcc, s59, v148
	s_cbranch_vccz .Lmla_norescale_2
; #define AT_QK_LD0(kb_) do { if constexpr (NEGM) { const LAS unsigned char* kbp_ = Kl + (kb_) * KBUF + r32 * KROWB + hi * 16; AT_KLD2(0); __builtin_amdgcn_sched_barrier(0); } } while (0)
; template <int DQK, int DV, int RH, bool NEGM> ...
;     ...
;     const int NT = nkv / 64;
;     AT_GLOAD(0); AT_LSTORE(0, 0); __syncthreads();
;     int vs_prev = 2, vs_cur = 0, vs_next = 1;
;     if (!grpB) {
;         for (int t = 0; t < NT; ++t) {
;             const int kb = t & 1;
;             if (t + 1 < NT) AT_GLOAD(t + 1);
;             f32x16 p[RH][2];
;             AT_QK_LD0(kb); AT_QK(kb); AT_VLOAD(vs_cur); AT_SOFTMAX(); AT_PV(vs_cur);
;             if (t + 1 < NT) AT_LSTORE(kb ^ 1, vs_next);
;             __syncthreads();
;             vs_prev = vs_cur; vs_cur = vs_next; vs_next = (vs_next == 2) ? 0 : vs_next + 1;
	v_mov_b32_e32 v160, v148
	s_nop 1
	v_permlane32_swap_b32_e32 v148, v160
	v_max_f32_e32 v148, v148, v160
	v_max_f32_e32 v32, v148, v148
	v_max_f32_e32 v148, 0, v32
	v_exp_f32_e64 v160, -v148
	v_add_f32_e32 v168, v168, v148
	v_xor_b32_e32 v32, 0x80000000, v168
	v_mov_b32_e32 v33, v32
	v_mov_b32_e32 v34, v32
	v_mov_b32_e32 v35, v32
	v_mov_b32_e32 v36, v32
	v_mov_b32_e32 v37, v32
	v_mov_b32_e32 v38, v32
	v_mov_b32_e32 v39, v32
	v_mov_b32_e32 v40, v32
	v_mov_b32_e32 v41, v32
	v_mov_b32_e32 v42, v32
	v_mov_b32_e32 v43, v32
	v_mov_b32_e32 v44, v32
	v_mov_b32_e32 v45, v32
	v_mov_b32_e32 v46, v32
	v_mov_b32_e32 v47, v32
	v_pk_add_f32 v[64:65], v[64:65], v[148:149] op_sel_hi:[1,0] neg_lo:[0,1] neg_hi:[0,1]
	v_pk_add_f32 v[48:49], v[48:49], v[148:149] op_sel_hi:[1,0] neg_lo:[0,1] neg_hi:[0,1]
	v_pk_add_f32 v[66:67], v[66:67], v[148:149] op_sel_hi:[1,0] neg_lo:[0,1] neg_hi:[0,1]
	v_pk_add_f32 v[50:51], v[50:51], v[148:149] op_sel_hi:[1,0] neg_lo:[0,1] neg_hi:[0,1]
	v_pk_add_f32 v[68:69], v[68:69], v[148:149] op_sel_hi:[1,0] neg_lo:[0,1] neg_hi:[0,1]
	v_pk_add_f32 v[52:53], v[52:53], v[148:149] op_sel_hi:[1,0] neg_lo:[0,1] neg_hi:[0,1]
	v_pk_add_f32 v[70:71], v[70:71], v[148:149] op_sel_hi:[1,0] neg_lo:[0,1] neg_hi:[0,1]
	v_pk_add_f32 v[54:55], v[54:55], v[148:149] op_sel_hi:[1,0] neg_lo:[0,1] neg_hi:[0,1]
	v_pk_add_f32 v[72:73], v[72:73], v[148:149] op_sel_hi:[1,0] neg_lo:[0,1] neg_hi:[0,1]
	v_pk_add_f32 v[56:57], v[56:57], v[148:149] op_sel_hi:[1,0] neg_lo:[0,1] neg_hi:[0,1]
	v_pk_add_f32 v[74:75], v[74:75], v[148:149] op_sel_hi:[1,0] neg_lo:[0,1] neg_hi:[0,1]
	v_pk_add_f32 v[58:59], v[58:59], v[148:149] op_sel_hi:[1,0] neg_lo:[0,1] neg_hi:[0,1]
	v_pk_add_f32 v[76:77], v[76:77], v[148:149] op_sel_hi:[1,0] neg_lo:[0,1] neg_hi:[0,1]
	v_pk_add_f32 v[60:61], v[60:61], v[148:149] op_sel_hi:[1,0] neg_lo:[0,1] neg_hi:[0,1]
	v_pk_add_f32 v[78:79], v[78:79], v[148:149] op_sel_hi:[1,0] neg_lo:[0,1] neg_hi:[0,1]
	v_pk_add_f32 v[62:63], v[62:63], v[148:149] op_sel_hi:[1,0] neg_lo:[0,1] neg_hi:[0,1]
	v_pk_mul_f32 v[30:31], v[30:31], v[160:161] op_sel_hi:[1,0]
	v_pk_mul_f32 v[28:29], v[28:29], v[160:161] op_sel_hi:[1,0]
	v_pk_mul_f32 v[26:27], v[26:27], v[160:161] op_sel_hi:[1,0]
	v_pk_mul_f32 v[24:25], v[24:25], v[160:161] op_sel_hi:[1,0]
	v_pk_mul_f32 v[22:23], v[22:23], v[160:161] op_sel_hi:[1,0]
	v_pk_mul_f32 v[20:21], v[20:21], v[160:161] op_sel_hi:[1,0]
	v_pk_mul_f32 v[18:19], v[18:19], v[160:161] op_sel_hi:[1,0]
	v_pk_mul_f32 v[16:17], v[16:17], v[160:161] op_sel_hi:[1,0]
	v_pk_mul_f32 v[14:15], v[14:15], v[160:161] op_sel_hi:[1,0]
	v_pk_mul_f32 v[12:13], v[12:13], v[160:161] op_sel_hi:[1,0]
	v_pk_mul_f32 v[10:11], v[10:11], v[160:161] op_sel_hi:[1,0]
	v_pk_mul_f32 v[8:9], v[8:9], v[160:161] op_sel_hi:[1,0]
	v_pk_mul_f32 v[6:7], v[6:7], v[160:161] op_sel_hi:[1,0]
	v_pk_mul_f32 v[4:5], v[4:5], v[160:161] op_sel_hi:[1,0]
	v_pk_mul_f32 v[2:3], v[2:3], v[160:161] op_sel_hi:[1,0]
	v_pk_mul_f32 v[0:1], v[0:1], v[160:161] op_sel_hi:[1,0]
	v_pk_mul_f32 v[152:153], v[152:153], v[160:161] op_sel_hi:[1,0]
	v_pk_mul_f32 v[150:151], v[150:151], v[160:161] op_sel_hi:[1,0]
.Lmla_norescale_2:
	v_exp_f32_e32 v160, v64
	v_exp_f32_e32 v161, v65
	v_exp_f32_e32 v64, v66
	v_exp_f32_e32 v65, v67
	v_exp_f32_e32 v68, v68
	v_exp_f32_e32 v69, v69
	v_exp_f32_e32 v66, v70
	v_exp_f32_e32 v67, v71
	v_cvt_pk_bf16_f32 v176, v160, v161
	v_cvt_pk_bf16_f32 v177, v64, v65
	v_cvt_pk_bf16_f32 v178, v68, v69
	v_cvt_pk_bf16_f32 v179, v66, v67
	v_exp_f32_e32 v70, v74
	v_exp_f32_e32 v71, v75
	s_waitcnt lgkmcnt(0)
	v_mfma_f32_32x32x16_bf16 v[16:31], v[136:139], v[176:179], v[16:31]
	v_exp_f32_e32 v136, v72
	v_exp_f32_e32 v137, v73
	v_exp_f32_e32 v74, v76
	v_exp_f32_e32 v75, v77
	v_exp_f32_e32 v72, v78
	v_exp_f32_e32 v73, v79
	v_exp_f32_e32 v76, v48
	v_mfma_f32_32x32x16_bf16 v[0:15], v[144:147], v[176:179], v[0:15]
	v_cvt_pk_bf16_f32 v144, v136, v137
	v_cvt_pk_bf16_f32 v145, v70, v71
	v_cvt_pk_bf16_f32 v146, v74, v75
	v_cvt_pk_bf16_f32 v147, v72, v73
	v_exp_f32_e32 v77, v49
	v_exp_f32_e32 v48, v50
	v_exp_f32_e32 v49, v51
	v_mfma_f32_32x32x16_bf16 v[16:31], v[124:127], v[144:147], v[16:31]
	v_exp_f32_e32 v52, v52
	v_exp_f32_e32 v53, v53
	v_exp_f32_e32 v50, v54
	v_exp_f32_e32 v51, v55
	v_cvt_pk_bf16_f32 v124, v76, v77
	v_cvt_pk_bf16_f32 v125, v48, v49
	v_cvt_pk_bf16_f32 v126, v52, v53
	v_mfma_f32_32x32x16_bf16 v[0:15], v[140:143], v[144:147], v[0:15]
	v_cvt_pk_bf16_f32 v127, v50, v51
	v_exp_f32_e32 v78, v56
	v_exp_f32_e32 v79, v57
	v_exp_f32_e32 v54, v58
	v_exp_f32_e32 v55, v59
	v_exp_f32_e32 v58, v60
	v_exp_f32_e32 v59, v61
	v_mfma_f32_32x32x16_bf16 v[16:31], v[132:135], v[124:127], v[16:31]
	v_exp_f32_e32 v56, v62
	v_exp_f32_e32 v57, v63
	v_cvt_pk_bf16_f32 v60, v78, v79
	v_cvt_pk_bf16_f32 v61, v54, v55
	v_cvt_pk_bf16_f32 v62, v58, v59
	v_cvt_pk_bf16_f32 v63, v56, v57
	v_mfma_f32_32x32x16_bf16 v[0:15], v[128:131], v[124:127], v[0:15]
	v_mfma_f32_32x32x16_bf16 v[16:31], v[120:123], v[60:63], v[16:31]
	v_mfma_f32_32x32x16_bf16 v[0:15], v[116:119], v[60:63], v[0:15]
	s_waitcnt vmcnt(1)
	ds_write_b128 v244, v[104:107] offset:13312
	s_mov_b64 exec, s[8:9]
	ds_write_b128 v245, v[108:111] offset:13312
	s_mov_b64 exec, -1
	s_waitcnt vmcnt(0)
	ds_write2_b64 v243, v[112:113], v[114:115] offset1:2
	v_pk_add_f32 v[48:49], v[64:65], v[48:49]
	v_pk_add_f32 v[60:61], v[160:161], v[76:77]
	v_pk_add_f32 v[48:49], v[152:153], v[48:49]
	v_pk_add_f32 v[50:51], v[66:67], v[50:51]
	v_pk_add_f32 v[60:61], v[150:151], v[60:61]
	v_pk_add_f32 v[52:53], v[68:69], v[52:53]
	v_pk_add_f32 v[48:49], v[50:51], v[48:49]
	v_pk_add_f32 v[50:51], v[70:71], v[54:55]
	v_pk_add_f32 v[52:53], v[52:53], v[60:61]
	v_pk_add_f32 v[60:61], v[136:137], v[78:79]
	v_pk_add_f32 v[48:49], v[50:51], v[48:49]
	v_pk_add_f32 v[50:51], v[72:73], v[56:57]
	v_pk_add_f32 v[52:53], v[60:61], v[52:53]
	v_pk_add_f32 v[58:59], v[74:75], v[58:59]
	v_pk_add_f32 v[152:153], v[50:51], v[48:49]
	v_pk_add_f32 v[150:151], v[58:59], v[52:53]
	s_cmp_lg_u32 s43, 63
	s_waitcnt lgkmcnt(0)
	s_barrier
	s_cbranch_scc0 .Lmla_exit
	global_load_dwordx4 v[104:107], v154, s[98:99]
	s_mov_b64 exec, s[8:9]
	global_load_dwordx4 v[108:111], v156, s[98:99]
	s_mov_b64 exec, -1
	global_load_dwordx4 v[112:115], v158, s[100:101]
	s_add_u32 s98, s98, 0x18000
	s_addc_u32 s99, s99, 0
	s_add_u32 s100, s100, 0x80
	s_addc_u32 s101, s101, 0
	ds_read_b128 v[48:51], v169 offset:13312
	ds_read_b128 v[52:55], v169 offset:13344
	ds_read_b128 v[116:119], v169 offset:19968
	ds_read_b128 v[120:123], v169 offset:20000
	s_waitcnt lgkmcnt(3)
	v_mfma_f32_32x32x16_bf16 v[64:79], v[48:51], v[100:103], v[32:47]
	ds_read_b128 v[124:127], v169 offset:13376
	ds_read_b128 v[128:131], v169 offset:13408
	ds_read_b128 v[132:135], v169 offset:20032
	ds_read_b128 v[136:139], v169 offset:20064
	s_waitcnt lgkmcnt(4)
	v_mfma_f32_32x32x16_bf16 v[64:79], v[52:55], v[96:99], v[64:79]
	v_mfma_f32_32x32x16_bf16 v[48:63], v[116:119], v[100:103], v[32:47]
	v_mfma_f32_32x32x16_bf16 v[48:63], v[120:123], v[96:99], v[48:63]
	s_waitcnt lgkmcnt(1)
	v_mfma_f32_32x32x16_bf16 v[64:79], v[124:127], v[92:95], v[64:79]
	v_mfma_f32_32x32x16_bf16 v[48:63], v[132:135], v[92:95], v[48:63]
	v_mfma_f32_32x32x16_bf16 v[64:79], v[128:131], v[88:91], v[64:79]
	ds_read_b128 v[116:119], v169 offset:13440
	ds_read_b128 v[120:123], v169 offset:13472
	ds_read_b128 v[128:131], v169 offset:20096
	ds_read_b128 v[176:179], v169 offset:20128
	s_waitcnt lgkmcnt(3)
	v_mfma_f32_32x32x16_bf16 v[48:63], v[136:139], v[88:91], v[48:63]
	v_mfma_f32_32x32x16_bf16 v[64:79], v[116:119], v[84:87], v[64:79]
	ds_read_b128 v[136:139], v170 offset:26624
	ds_read_b128 v[124:127], v170 offset:26656
	s_waitcnt lgkmcnt(3)
	v_mfma_f32_32x32x16_bf16 v[48:63], v[128:131], v[84:87], v[48:63]
	v_mfma_f32_32x32x16_bf16 v[64:79], v[120:123], v[80:83], v[64:79]
	ds_read_b128 v[132:135], v170 offset:26688
	ds_read_b128 v[120:123], v170 offset:26720
	ds_read_b128 v[144:147], v170 offset:31232
	ds_read_b128 v[140:143], v170 offset:31264
	ds_read_b128 v[128:131], v170 offset:31296
	ds_read_b128 v[116:119], v170 offset:31328
	s_waitcnt lgkmcnt(8)
	v_mfma_f32_32x32x16_bf16 v[48:63], v[176:179], v[80:83], v[48:63]
	s_add_i32 s43, s43, 1
	s_nop 10
	v_max_f32_e32 v148, v64, v48
	v_max_f32_e32 v160, v65, v49
	v_max_f32_e32 v161, v67, v51
	v_max3_f32 v176, v66, v50, v70
	v_max3_f32 v161, v161, v71, v55
	v_max3_f32 v148, v148, v68, v52
	v_max3_f32 v160, v160, v69, v53
	v_max3_f32 v176, v176, v54, v74
	v_max3_f32 v161, v161, v75, v59
	v_max3_f32 v148, v148, v72, v56
	v_max3_f32 v160, v160, v73, v57
	v_max3_f32 v176, v176, v58, v78
	v_max3_f32 v161, v161, v79, v63
	v_max3_f32 v148, v148, v76, v60
	v_max3_f32 v160, v160, v77, v61
	v_max3_f32 v161, v176, v62, v161
	v_max3_f32 v148, v148, v160, v161
	v_cmp_lt_f32_e32 vcc, s59, v148
	s_cbranch_vccz .Lmla_norescale_3
	v_mov_b32_e32 v160, v148
	s_nop 1
	v_permlane32_swap_b32_e32 v148, v160
	v_max_f32_e32 v148, v148, v160
	v_max_f32_e32 v32, v148, v148
	v_max_f32_e32 v148, 0, v32
	v_exp_f32_e64 v160, -v148
	v_add_f32_e32 v168, v168, v148
	v_xor_b32_e32 v32, 0x80000000, v168
	v_mov_b32_e32 v33, v32
	v_mov_b32_e32 v34, v32
	v_mov_b32_e32 v35, v32
	v_mov_b32_e32 v36, v32
	v_mov_b32_e32 v37, v32
	v_mov_b32_e32 v38, v32
	v_mov_b32_e32 v39, v32
	v_mov_b32_e32 v40, v32
	v_mov_b32_e32 v41, v32
	v_mov_b32_e32 v42, v32
	v_mov_b32_e32 v43, v32
	v_mov_b32_e32 v44, v32
	v_mov_b32_e32 v45, v32
	v_mov_b32_e32 v46, v32
	v_mov_b32_e32 v47, v32
	v_pk_add_f32 v[64:65], v[64:65], v[148:149] op_sel_hi:[1,0] neg_lo:[0,1] neg_hi:[0,1]
	v_pk_add_f32 v[48:49], v[48:49], v[148:149] op_sel_hi:[1,0] neg_lo:[0,1] neg_hi:[0,1]
	v_pk_add_f32 v[66:67], v[66:67], v[148:149] op_sel_hi:[1,0] neg_lo:[0,1] neg_hi:[0,1]
	v_pk_add_f32 v[50:51], v[50:51], v[148:149] op_sel_hi:[1,0] neg_lo:[0,1] neg_hi:[0,1]
	v_pk_add_f32 v[68:69], v[68:69], v[148:149] op_sel_hi:[1,0] neg_lo:[0,1] neg_hi:[0,1]
	v_pk_add_f32 v[52:53], v[52:53], v[148:149] op_sel_hi:[1,0] neg_lo:[0,1] neg_hi:[0,1]
	v_pk_add_f32 v[70:71], v[70:71], v[148:149] op_sel_hi:[1,0] neg_lo:[0,1] neg_hi:[0,1]
	v_pk_add_f32 v[54:55], v[54:55], v[148:149] op_sel_hi:[1,0] neg_lo:[0,1] neg_hi:[0,1]
	v_pk_add_f32 v[72:73], v[72:73], v[148:149] op_sel_hi:[1,0] neg_lo:[0,1] neg_hi:[0,1]
	v_pk_add_f32 v[56:57], v[56:57], v[148:149] op_sel_hi:[1,0] neg_lo:[0,1] neg_hi:[0,1]
	v_pk_add_f32 v[74:75], v[74:75], v[148:149] op_sel_hi:[1,0] neg_lo:[0,1] neg_hi:[0,1]
	v_pk_add_f32 v[58:59], v[58:59], v[148:149] op_sel_hi:[1,0] neg_lo:[0,1] neg_hi:[0,1]
	v_pk_add_f32 v[76:77], v[76:77], v[148:149] op_sel_hi:[1,0] neg_lo:[0,1] neg_hi:[0,1]
	v_pk_add_f32 v[60:61], v[60:61], v[148:149] op_sel_hi:[1,0] neg_lo:[0,1] neg_hi:[0,1]
	v_pk_add_f32 v[78:79], v[78:79], v[148:149] op_sel_hi:[1,0] neg_lo:[0,1] neg_hi:[0,1]
	v_pk_add_f32 v[62:63], v[62:63], v[148:149] op_sel_hi:[1,0] neg_lo:[0,1] neg_hi:[0,1]
	v_pk_mul_f32 v[30:31], v[30:31], v[160:161] op_sel_hi:[1,0]
	v_pk_mul_f32 v[28:29], v[28:29], v[160:161] op_sel_hi:[1,0]
	v_pk_mul_f32 v[26:27], v[26:27], v[160:161] op_sel_hi:[1,0]
	v_pk_mul_f32 v[24:25], v[24:25], v[160:161] op_sel_hi:[1,0]
	v_pk_mul_f32 v[22:23], v[22:23], v[160:161] op_sel_hi:[1,0]
	v_pk_mul_f32 v[20:21], v[20:21], v[160:161] op_sel_hi:[1,0]
	v_pk_mul_f32 v[18:19], v[18:19], v[160:161] op_sel_hi:[1,0]
	v_pk_mul_f32 v[16:17], v[16:17], v[160:161] op_sel_hi:[1,0]
	v_pk_mul_f32 v[14:15], v[14:15], v[160:161] op_sel_hi:[1,0]
	v_pk_mul_f32 v[12:13], v[12:13], v[160:161] op_sel_hi:[1,0]
	v_pk_mul_f32 v[10:11], v[10:11], v[160:161] op_sel_hi:[1,0]
	v_pk_mul_f32 v[8:9], v[8:9], v[160:161] op_sel_hi:[1,0]
	v_pk_mul_f32 v[6:7], v[6:7], v[160:161] op_sel_hi:[1,0]
	v_pk_mul_f32 v[4:5], v[4:5], v[160:161] op_sel_hi:[1,0]
	v_pk_mul_f32 v[2:3], v[2:3], v[160:161] op_sel_hi:[1,0]
	v_pk_mul_f32 v[0:1], v[0:1], v[160:161] op_sel_hi:[1,0]
	v_pk_mul_f32 v[152:153], v[152:153], v[160:161] op_sel_hi:[1,0]
	v_pk_mul_f32 v[150:151], v[150:151], v[160:161] op_sel_hi:[1,0]
; #define AT_QK_LD0(kb_) do { if constexpr (NEGM) { const LAS unsigned char* kbp_ = Kl + (kb_) * KBUF + r32 * KROWB + hi * 16; AT_KLD2(0); __builtin_amdgcn_sched_barrier(0); } } while (0)
; template <int DQK, int DV, int RH, bool NEGM> ...
;     ...
;     const int NT = nkv / 64;
;     AT_GLOAD(0); AT_LSTORE(0, 0); __syncthreads();
;     int vs_prev = 2, vs_cur = 0, vs_next = 1;
;     if (!grpB) {
;         for (int t = 0; t < NT; ++t) {
;             const int kb = t & 1;
;             if (t + 1 < NT) AT_GLOAD(t + 1);
;             f32x16 p[RH][2];
;             AT_QK_LD0(kb); AT_QK(kb); AT_VLOAD(vs_cur); AT_SOFTMAX(); AT_PV(vs_cur);
;             if (t + 1 < NT) AT_LSTORE(kb ^ 1, vs_next);
;             __syncthreads();
;             vs_prev = vs_cur; vs_cur = vs_next; vs_next = (vs_next == 2) ? 0 : vs_next + 1;
.Lmla_norescale_3:
	v_exp_f32_e32 v160, v64
	v_exp_f32_e32 v161, v65
	v_exp_f32_e32 v64, v66
	v_exp_f32_e32 v65, v67
	v_exp_f32_e32 v68, v68
	v_exp_f32_e32 v69, v69
	v_exp_f32_e32 v66, v70
	v_exp_f32_e32 v67, v71
	v_cvt_pk_bf16_f32 v176, v160, v161
	v_cvt_pk_bf16_f32 v177, v64, v65
	v_cvt_pk_bf16_f32 v178, v68, v69
	v_cvt_pk_bf16_f32 v179, v66, v67
	v_exp_f32_e32 v70, v74
	v_exp_f32_e32 v71, v75
	s_waitcnt lgkmcnt(0)
	v_mfma_f32_32x32x16_bf16 v[16:31], v[136:139], v[176:179], v[16:31]
	v_exp_f32_e32 v136, v72
	v_exp_f32_e32 v137, v73
	v_exp_f32_e32 v74, v76
	v_exp_f32_e32 v75, v77
	v_exp_f32_e32 v72, v78
	v_exp_f32_e32 v73, v79
	v_exp_f32_e32 v76, v48
	v_mfma_f32_32x32x16_bf16 v[0:15], v[144:147], v[176:179], v[0:15]
	v_cvt_pk_bf16_f32 v144, v136, v137
	v_cvt_pk_bf16_f32 v145, v70, v71
	v_cvt_pk_bf16_f32 v146, v74, v75
	v_cvt_pk_bf16_f32 v147, v72, v73
	v_exp_f32_e32 v77, v49
	v_exp_f32_e32 v48, v50
	v_exp_f32_e32 v49, v51
	v_mfma_f32_32x32x16_bf16 v[16:31], v[124:127], v[144:147], v[16:31]
	v_exp_f32_e32 v52, v52
	v_exp_f32_e32 v53, v53
	v_exp_f32_e32 v50, v54
	v_exp_f32_e32 v51, v55
	v_cvt_pk_bf16_f32 v124, v76, v77
	v_cvt_pk_bf16_f32 v125, v48, v49
	v_cvt_pk_bf16_f32 v126, v52, v53
	v_mfma_f32_32x32x16_bf16 v[0:15], v[140:143], v[144:147], v[0:15]
	v_cvt_pk_bf16_f32 v127, v50, v51
	v_exp_f32_e32 v78, v56
	v_exp_f32_e32 v79, v57
	v_exp_f32_e32 v54, v58
	v_exp_f32_e32 v55, v59
	v_exp_f32_e32 v58, v60
	v_exp_f32_e32 v59, v61
	v_mfma_f32_32x32x16_bf16 v[16:31], v[132:135], v[124:127], v[16:31]
	v_exp_f32_e32 v56, v62
	v_exp_f32_e32 v57, v63
	v_cvt_pk_bf16_f32 v60, v78, v79
	v_cvt_pk_bf16_f32 v61, v54, v55
	v_cvt_pk_bf16_f32 v62, v58, v59
	v_cvt_pk_bf16_f32 v63, v56, v57
	v_mfma_f32_32x32x16_bf16 v[0:15], v[128:131], v[124:127], v[0:15]
	v_mfma_f32_32x32x16_bf16 v[16:31], v[120:123], v[60:63], v[16:31]
	v_mfma_f32_32x32x16_bf16 v[0:15], v[116:119], v[60:63], v[0:15]
	s_waitcnt vmcnt(1)
	ds_write_b128 v244, v[104:107]
	s_mov_b64 exec, s[8:9]
	ds_write_b128 v245, v[108:111]
	s_mov_b64 exec, -1
	s_waitcnt vmcnt(0)
	ds_write2_b64 v246, v[112:113], v[114:115] offset1:2
	v_pk_add_f32 v[48:49], v[64:65], v[48:49]
	v_pk_add_f32 v[60:61], v[160:161], v[76:77]
	v_pk_add_f32 v[48:49], v[152:153], v[48:49]
	v_pk_add_f32 v[50:51], v[66:67], v[50:51]
	v_pk_add_f32 v[60:61], v[150:151], v[60:61]
	v_pk_add_f32 v[52:53], v[68:69], v[52:53]
	v_pk_add_f32 v[48:49], v[50:51], v[48:49]
	v_pk_add_f32 v[50:51], v[70:71], v[54:55]
	v_pk_add_f32 v[52:53], v[52:53], v[60:61]
	v_pk_add_f32 v[60:61], v[136:137], v[78:79]
	v_pk_add_f32 v[48:49], v[50:51], v[48:49]
	v_pk_add_f32 v[50:51], v[72:73], v[56:57]
	v_pk_add_f32 v[52:53], v[60:61], v[52:53]
	v_pk_add_f32 v[58:59], v[74:75], v[58:59]
	v_pk_add_f32 v[152:153], v[50:51], v[48:49]
	v_pk_add_f32 v[150:151], v[58:59], v[52:53]
	s_waitcnt lgkmcnt(0)
	s_barrier
	global_load_dwordx4 v[104:107], v154, s[98:99]
	s_mov_b64 exec, s[8:9]
	global_load_dwordx4 v[108:111], v156, s[98:99]
	s_mov_b64 exec, -1
	global_load_dwordx4 v[112:115], v158, s[100:101]
	s_add_u32 s98, s98, 0x18000
	s_addc_u32 s99, s99, 0
	s_add_u32 s100, s100, 0x80
	s_addc_u32 s101, s101, 0
	ds_read_b128 v[48:51], v169
	ds_read_b128 v[52:55], v169 offset:32
	ds_read_b128 v[116:119], v169 offset:6656
	ds_read_b128 v[120:123], v169 offset:6688
	s_waitcnt lgkmcnt(3)
	v_mfma_f32_32x32x16_bf16 v[64:79], v[48:51], v[100:103], v[32:47]
	ds_read_b128 v[124:127], v169 offset:64
	ds_read_b128 v[128:131], v169 offset:96
	ds_read_b128 v[132:135], v169 offset:6720
	ds_read_b128 v[136:139], v169 offset:6752
	s_waitcnt lgkmcnt(4)
	v_mfma_f32_32x32x16_bf16 v[64:79], v[52:55], v[96:99], v[64:79]
	v_mfma_f32_32x32x16_bf16 v[48:63], v[116:119], v[100:103], v[32:47]
	v_mfma_f32_32x32x16_bf16 v[48:63], v[120:123], v[96:99], v[48:63]
	s_waitcnt lgkmcnt(1)
	v_mfma_f32_32x32x16_bf16 v[64:79], v[124:127], v[92:95], v[64:79]
	v_mfma_f32_32x32x16_bf16 v[48:63], v[132:135], v[92:95], v[48:63]
	v_mfma_f32_32x32x16_bf16 v[64:79], v[128:131], v[88:91], v[64:79]
	ds_read_b128 v[116:119], v169 offset:128
	ds_read_b128 v[120:123], v169 offset:160
	ds_read_b128 v[128:131], v169 offset:6784
	ds_read_b128 v[176:179], v169 offset:6816
	s_waitcnt lgkmcnt(3)
	v_mfma_f32_32x32x16_bf16 v[48:63], v[136:139], v[88:91], v[48:63]
	v_mfma_f32_32x32x16_bf16 v[64:79], v[116:119], v[84:87], v[64:79]
	ds_read_b128 v[136:139], v170 offset:35840
	ds_read_b128 v[124:127], v170 offset:35872
	s_waitcnt lgkmcnt(3)
	v_mfma_f32_32x32x16_bf16 v[48:63], v[128:131], v[84:87], v[48:63]
	v_mfma_f32_32x32x16_bf16 v[64:79], v[120:123], v[80:83], v[64:79]
	ds_read_b128 v[132:135], v170 offset:35904
	ds_read_b128 v[120:123], v170 offset:35936
	ds_read_b128 v[144:147], v170 offset:40448
	ds_read_b128 v[140:143], v170 offset:40480
	ds_read_b128 v[128:131], v170 offset:40512
	ds_read_b128 v[116:119], v170 offset:40544
	s_waitcnt lgkmcnt(8)
	v_mfma_f32_32x32x16_bf16 v[48:63], v[176:179], v[80:83], v[48:63]
	s_add_i32 s43, s43, 1
	s_nop 10
	v_max_f32_e32 v148, v64, v48
	v_max_f32_e32 v160, v65, v49
	v_max_f32_e32 v161, v67, v51
	v_max3_f32 v176, v66, v50, v70
	v_max3_f32 v161, v161, v71, v55
	v_max3_f32 v148, v148, v68, v52
	v_max3_f32 v160, v160, v69, v53
	v_max3_f32 v176, v176, v54, v74
	v_max3_f32 v161, v161, v75, v59
	v_max3_f32 v148, v148, v72, v56
	v_max3_f32 v160, v160, v73, v57
	v_max3_f32 v176, v176, v58, v78
	v_max3_f32 v161, v161, v79, v63
	v_max3_f32 v148, v148, v76, v60
	v_max3_f32 v160, v160, v77, v61
	v_max3_f32 v161, v176, v62, v161
	v_max3_f32 v148, v148, v160, v161
	v_cmp_lt_f32_e32 vcc, s59, v148
	s_cbranch_vccz .Lmla_norescale_4
; #define AT_QK_LD0(kb_) do { if constexpr (NEGM) { const LAS unsigned char* kbp_ = Kl + (kb_) * KBUF + r32 * KROWB + hi * 16; AT_KLD2(0); __builtin_amdgcn_sched_barrier(0); } } while (0)
; template <int DQK, int DV, int RH, bool NEGM> ...
;     ...
;     const int NT = nkv / 64;
;     AT_GLOAD(0); AT_LSTORE(0, 0); __syncthreads();
;     int vs_prev = 2, vs_cur = 0, vs_next = 1;
;     if (!grpB) {
;         for (int t = 0; t < NT; ++t) {
;             const int kb = t & 1;
;             if (t + 1 < NT) AT_GLOAD(t + 1);
;             f32x16 p[RH][2];
;             AT_QK_LD0(kb); AT_QK(kb); AT_VLOAD(vs_cur); AT_SOFTMAX(); AT_PV(vs_cur);
;             if (t + 1 < NT) AT_LSTORE(kb ^ 1, vs_next);
;             __syncthreads();
;             vs_prev = vs_cur; vs_cur = vs_next; vs_next = (vs_next == 2) ? 0 : vs_next + 1;
	v_mov_b32_e32 v160, v148
	s_nop 1
	v_permlane32_swap_b32_e32 v148, v160
	v_max_f32_e32 v148, v148, v160
	v_max_f32_e32 v32, v148, v148
	v_max_f32_e32 v148, 0, v32
	v_exp_f32_e64 v160, -v148
	v_add_f32_e32 v168, v168, v148
	v_xor_b32_e32 v32, 0x80000000, v168
	v_mov_b32_e32 v33, v32
	v_mov_b32_e32 v34, v32
	v_mov_b32_e32 v35, v32
	v_mov_b32_e32 v36, v32
	v_mov_b32_e32 v37, v32
	v_mov_b32_e32 v38, v32
	v_mov_b32_e32 v39, v32
	v_mov_b32_e32 v40, v32
	v_mov_b32_e32 v41, v32
	v_mov_b32_e32 v42, v32
	v_mov_b32_e32 v43, v32
	v_mov_b32_e32 v44, v32
	v_mov_b32_e32 v45, v32
	v_mov_b32_e32 v46, v32
	v_mov_b32_e32 v47, v32
	v_pk_add_f32 v[64:65], v[64:65], v[148:149] op_sel_hi:[1,0] neg_lo:[0,1] neg_hi:[0,1]
	v_pk_add_f32 v[48:49], v[48:49], v[148:149] op_sel_hi:[1,0] neg_lo:[0,1] neg_hi:[0,1]
	v_pk_add_f32 v[66:67], v[66:67], v[148:149] op_sel_hi:[1,0] neg_lo:[0,1] neg_hi:[0,1]
	v_pk_add_f32 v[50:51], v[50:51], v[148:149] op_sel_hi:[1,0] neg_lo:[0,1] neg_hi:[0,1]
	v_pk_add_f32 v[68:69], v[68:69], v[148:149] op_sel_hi:[1,0] neg_lo:[0,1] neg_hi:[0,1]
	v_pk_add_f32 v[52:53], v[52:53], v[148:149] op_sel_hi:[1,0] neg_lo:[0,1] neg_hi:[0,1]
	v_pk_add_f32 v[70:71], v[70:71], v[148:149] op_sel_hi:[1,0] neg_lo:[0,1] neg_hi:[0,1]
	v_pk_add_f32 v[54:55], v[54:55], v[148:149] op_sel_hi:[1,0] neg_lo:[0,1] neg_hi:[0,1]
	v_pk_add_f32 v[72:73], v[72:73], v[148:149] op_sel_hi:[1,0] neg_lo:[0,1] neg_hi:[0,1]
	v_pk_add_f32 v[56:57], v[56:57], v[148:149] op_sel_hi:[1,0] neg_lo:[0,1] neg_hi:[0,1]
	v_pk_add_f32 v[74:75], v[74:75], v[148:149] op_sel_hi:[1,0] neg_lo:[0,1] neg_hi:[0,1]
	v_pk_add_f32 v[58:59], v[58:59], v[148:149] op_sel_hi:[1,0] neg_lo:[0,1] neg_hi:[0,1]
	v_pk_add_f32 v[76:77], v[76:77], v[148:149] op_sel_hi:[1,0] neg_lo:[0,1] neg_hi:[0,1]
	v_pk_add_f32 v[60:61], v[60:61], v[148:149] op_sel_hi:[1,0] neg_lo:[0,1] neg_hi:[0,1]
	v_pk_add_f32 v[78:79], v[78:79], v[148:149] op_sel_hi:[1,0] neg_lo:[0,1] neg_hi:[0,1]
	v_pk_add_f32 v[62:63], v[62:63], v[148:149] op_sel_hi:[1,0] neg_lo:[0,1] neg_hi:[0,1]
	v_pk_mul_f32 v[30:31], v[30:31], v[160:161] op_sel_hi:[1,0]
	v_pk_mul_f32 v[28:29], v[28:29], v[160:161] op_sel_hi:[1,0]
	v_pk_mul_f32 v[26:27], v[26:27], v[160:161] op_sel_hi:[1,0]
	v_pk_mul_f32 v[24:25], v[24:25], v[160:161] op_sel_hi:[1,0]
	v_pk_mul_f32 v[22:23], v[22:23], v[160:161] op_sel_hi:[1,0]
	v_pk_mul_f32 v[20:21], v[20:21], v[160:161] op_sel_hi:[1,0]
	v_pk_mul_f32 v[18:19], v[18:19], v[160:161] op_sel_hi:[1,0]
	v_pk_mul_f32 v[16:17], v[16:17], v[160:161] op_sel_hi:[1,0]
	v_pk_mul_f32 v[14:15], v[14:15], v[160:161] op_sel_hi:[1,0]
	v_pk_mul_f32 v[12:13], v[12:13], v[160:161] op_sel_hi:[1,0]
	v_pk_mul_f32 v[10:11], v[10:11], v[160:161] op_sel_hi:[1,0]
	v_pk_mul_f32 v[8:9], v[8:9], v[160:161] op_sel_hi:[1,0]
	v_pk_mul_f32 v[6:7], v[6:7], v[160:161] op_sel_hi:[1,0]
	v_pk_mul_f32 v[4:5], v[4:5], v[160:161] op_sel_hi:[1,0]
	v_pk_mul_f32 v[2:3], v[2:3], v[160:161] op_sel_hi:[1,0]
	v_pk_mul_f32 v[0:1], v[0:1], v[160:161] op_sel_hi:[1,0]
	v_pk_mul_f32 v[152:153], v[152:153], v[160:161] op_sel_hi:[1,0]
	v_pk_mul_f32 v[150:151], v[150:151], v[160:161] op_sel_hi:[1,0]
.Lmla_norescale_4:
	v_exp_f32_e32 v160, v64
	v_exp_f32_e32 v161, v65
	v_exp_f32_e32 v64, v66
	v_exp_f32_e32 v65, v67
	v_exp_f32_e32 v68, v68
	v_exp_f32_e32 v69, v69
	v_exp_f32_e32 v66, v70
	v_exp_f32_e32 v67, v71
	v_cvt_pk_bf16_f32 v176, v160, v161
	v_cvt_pk_bf16_f32 v177, v64, v65
	v_cvt_pk_bf16_f32 v178, v68, v69
	v_cvt_pk_bf16_f32 v179, v66, v67
	v_exp_f32_e32 v70, v74
	v_exp_f32_e32 v71, v75
	s_waitcnt lgkmcnt(0)
	v_mfma_f32_32x32x16_bf16 v[16:31], v[136:139], v[176:179], v[16:31]
	v_exp_f32_e32 v136, v72
	v_exp_f32_e32 v137, v73
	v_exp_f32_e32 v74, v76
	v_exp_f32_e32 v75, v77
	v_exp_f32_e32 v72, v78
	v_exp_f32_e32 v73, v79
	v_exp_f32_e32 v76, v48
	v_mfma_f32_32x32x16_bf16 v[0:15], v[144:147], v[176:179], v[0:15]
	v_cvt_pk_bf16_f32 v144, v136, v137
	v_cvt_pk_bf16_f32 v145, v70, v71
	v_cvt_pk_bf16_f32 v146, v74, v75
	v_cvt_pk_bf16_f32 v147, v72, v73
	v_exp_f32_e32 v77, v49
	v_exp_f32_e32 v48, v50
	v_exp_f32_e32 v49, v51
	v_mfma_f32_32x32x16_bf16 v[16:31], v[124:127], v[144:147], v[16:31]
	v_exp_f32_e32 v52, v52
	v_exp_f32_e32 v53, v53
	v_exp_f32_e32 v50, v54
	v_exp_f32_e32 v51, v55
	v_cvt_pk_bf16_f32 v124, v76, v77
	v_cvt_pk_bf16_f32 v125, v48, v49
	v_cvt_pk_bf16_f32 v126, v52, v53
	v_mfma_f32_32x32x16_bf16 v[0:15], v[140:143], v[144:147], v[0:15]
	v_cvt_pk_bf16_f32 v127, v50, v51
	v_exp_f32_e32 v78, v56
	v_exp_f32_e32 v79, v57
	v_exp_f32_e32 v54, v58
	v_exp_f32_e32 v55, v59
	v_exp_f32_e32 v58, v60
	v_exp_f32_e32 v59, v61
	v_mfma_f32_32x32x16_bf16 v[16:31], v[132:135], v[124:127], v[16:31]
	v_exp_f32_e32 v56, v62
	v_exp_f32_e32 v57, v63
	v_cvt_pk_bf16_f32 v60, v78, v79
	v_cvt_pk_bf16_f32 v61, v54, v55
	v_cvt_pk_bf16_f32 v62, v58, v59
	v_cvt_pk_bf16_f32 v63, v56, v57
	v_mfma_f32_32x32x16_bf16 v[0:15], v[128:131], v[124:127], v[0:15]
	v_mfma_f32_32x32x16_bf16 v[16:31], v[120:123], v[60:63], v[16:31]
	v_mfma_f32_32x32x16_bf16 v[0:15], v[116:119], v[60:63], v[0:15]
	s_waitcnt vmcnt(1)
	ds_write_b128 v244, v[104:107] offset:13312
	s_mov_b64 exec, s[8:9]
	ds_write_b128 v245, v[108:111] offset:13312
	s_mov_b64 exec, -1
	s_waitcnt vmcnt(0)
	ds_write2_b64 v247, v[112:113], v[114:115] offset1:2
	v_pk_add_f32 v[48:49], v[64:65], v[48:49]
	v_pk_add_f32 v[60:61], v[160:161], v[76:77]
	v_pk_add_f32 v[48:49], v[152:153], v[48:49]
	v_pk_add_f32 v[50:51], v[66:67], v[50:51]
	v_pk_add_f32 v[60:61], v[150:151], v[60:61]
	v_pk_add_f32 v[52:53], v[68:69], v[52:53]
	v_pk_add_f32 v[48:49], v[50:51], v[48:49]
	v_pk_add_f32 v[50:51], v[70:71], v[54:55]
	v_pk_add_f32 v[52:53], v[52:53], v[60:61]
	v_pk_add_f32 v[60:61], v[136:137], v[78:79]
	v_pk_add_f32 v[48:49], v[50:51], v[48:49]
	v_pk_add_f32 v[50:51], v[72:73], v[56:57]
	v_pk_add_f32 v[52:53], v[60:61], v[52:53]
	v_pk_add_f32 v[58:59], v[74:75], v[58:59]
	v_pk_add_f32 v[152:153], v[50:51], v[48:49]
	v_pk_add_f32 v[150:151], v[58:59], v[52:53]
	s_waitcnt lgkmcnt(0)
	s_barrier
	global_load_dwordx4 v[104:107], v154, s[98:99]
	s_mov_b64 exec, s[8:9]
	global_load_dwordx4 v[108:111], v156, s[98:99]
	s_mov_b64 exec, -1
	global_load_dwordx4 v[112:115], v158, s[100:101]
	s_add_u32 s98, s98, 0x18000
	s_addc_u32 s99, s99, 0
	s_add_u32 s100, s100, 0x80
	s_addc_u32 s101, s101, 0
	ds_read_b128 v[48:51], v169 offset:13312
	ds_read_b128 v[52:55], v169 offset:13344
	ds_read_b128 v[116:119], v169 offset:19968
	ds_read_b128 v[120:123], v169 offset:20000
	s_waitcnt lgkmcnt(3)
	v_mfma_f32_32x32x16_bf16 v[64:79], v[48:51], v[100:103], v[32:47]
	ds_read_b128 v[124:127], v169 offset:13376
	ds_read_b128 v[128:131], v169 offset:13408
	ds_read_b128 v[132:135], v169 offset:20032
	ds_read_b128 v[136:139], v169 offset:20064
	s_waitcnt lgkmcnt(4)
	v_mfma_f32_32x32x16_bf16 v[64:79], v[52:55], v[96:99], v[64:79]
	v_mfma_f32_32x32x16_bf16 v[48:63], v[116:119], v[100:103], v[32:47]
	v_mfma_f32_32x32x16_bf16 v[48:63], v[120:123], v[96:99], v[48:63]
	s_waitcnt lgkmcnt(1)
	v_mfma_f32_32x32x16_bf16 v[64:79], v[124:127], v[92:95], v[64:79]
	v_mfma_f32_32x32x16_bf16 v[48:63], v[132:135], v[92:95], v[48:63]
	v_mfma_f32_32x32x16_bf16 v[64:79], v[128:131], v[88:91], v[64:79]
	ds_read_b128 v[116:119], v169 offset:13440
	ds_read_b128 v[120:123], v169 offset:13472
	ds_read_b128 v[128:131], v169 offset:20096
	ds_read_b128 v[176:179], v169 offset:20128
	s_waitcnt lgkmcnt(3)
	v_mfma_f32_32x32x16_bf16 v[48:63], v[136:139], v[88:91], v[48:63]
	v_mfma_f32_32x32x16_bf16 v[64:79], v[116:119], v[84:87], v[64:79]
	ds_read_b128 v[136:139], v170 offset:45056
	ds_read_b128 v[124:127], v170 offset:45088
	s_waitcnt lgkmcnt(3)
	v_mfma_f32_32x32x16_bf16 v[48:63], v[128:131], v[84:87], v[48:63]
	v_mfma_f32_32x32x16_bf16 v[64:79], v[120:123], v[80:83], v[64:79]
	ds_read_b128 v[132:135], v170 offset:45120
	ds_read_b128 v[120:123], v170 offset:45152
	ds_read_b128 v[144:147], v170 offset:49664
	ds_read_b128 v[140:143], v170 offset:49696
	ds_read_b128 v[128:131], v170 offset:49728
	ds_read_b128 v[116:119], v170 offset:49760
	s_waitcnt lgkmcnt(8)
	v_mfma_f32_32x32x16_bf16 v[48:63], v[176:179], v[80:83], v[48:63]
	s_add_i32 s43, s43, 1
	s_nop 10
	v_max_f32_e32 v148, v64, v48
	v_max_f32_e32 v160, v65, v49
	v_max_f32_e32 v161, v67, v51
	v_max3_f32 v176, v66, v50, v70
	v_max3_f32 v161, v161, v71, v55
	v_max3_f32 v148, v148, v68, v52
	v_max3_f32 v160, v160, v69, v53
	v_max3_f32 v176, v176, v54, v74
	v_max3_f32 v161, v161, v75, v59
	v_max3_f32 v148, v148, v72, v56
	v_max3_f32 v160, v160, v73, v57
	v_max3_f32 v176, v176, v58, v78
	v_max3_f32 v161, v161, v79, v63
	v_max3_f32 v148, v148, v76, v60
	v_max3_f32 v160, v160, v77, v61
	v_max3_f32 v161, v176, v62, v161
	v_max3_f32 v148, v148, v160, v161
	v_cmp_lt_f32_e32 vcc, s59, v148
	s_cbranch_vccz .Lmla_norescale_5
	v_mov_b32_e32 v160, v148
	s_nop 1
	v_permlane32_swap_b32_e32 v148, v160
	v_max_f32_e32 v148, v148, v160
	v_max_f32_e32 v32, v148, v148
	v_max_f32_e32 v148, 0, v32
	v_exp_f32_e64 v160, -v148
	v_add_f32_e32 v168, v168, v148
	v_xor_b32_e32 v32, 0x80000000, v168
	v_mov_b32_e32 v33, v32
	v_mov_b32_e32 v34, v32
	v_mov_b32_e32 v35, v32
	v_mov_b32_e32 v36, v32
	v_mov_b32_e32 v37, v32
	v_mov_b32_e32 v38, v32
	v_mov_b32_e32 v39, v32
	v_mov_b32_e32 v40, v32
	v_mov_b32_e32 v41, v32
	v_mov_b32_e32 v42, v32
	v_mov_b32_e32 v43, v32
	v_mov_b32_e32 v44, v32
	v_mov_b32_e32 v45, v32
	v_mov_b32_e32 v46, v32
	v_mov_b32_e32 v47, v32
	v_pk_add_f32 v[64:65], v[64:65], v[148:149] op_sel_hi:[1,0] neg_lo:[0,1] neg_hi:[0,1]
	v_pk_add_f32 v[48:49], v[48:49], v[148:149] op_sel_hi:[1,0] neg_lo:[0,1] neg_hi:[0,1]
	v_pk_add_f32 v[66:67], v[66:67], v[148:149] op_sel_hi:[1,0] neg_lo:[0,1] neg_hi:[0,1]
	v_pk_add_f32 v[50:51], v[50:51], v[148:149] op_sel_hi:[1,0] neg_lo:[0,1] neg_hi:[0,1]
	v_pk_add_f32 v[68:69], v[68:69], v[148:149] op_sel_hi:[1,0] neg_lo:[0,1] neg_hi:[0,1]
	v_pk_add_f32 v[52:53], v[52:53], v[148:149] op_sel_hi:[1,0] neg_lo:[0,1] neg_hi:[0,1]
	v_pk_add_f32 v[70:71], v[70:71], v[148:149] op_sel_hi:[1,0] neg_lo:[0,1] neg_hi:[0,1]
	v_pk_add_f32 v[54:55], v[54:55], v[148:149] op_sel_hi:[1,0] neg_lo:[0,1] neg_hi:[0,1]
	v_pk_add_f32 v[72:73], v[72:73], v[148:149] op_sel_hi:[1,0] neg_lo:[0,1] neg_hi:[0,1]
	v_pk_add_f32 v[56:57], v[56:57], v[148:149] op_sel_hi:[1,0] neg_lo:[0,1] neg_hi:[0,1]
	v_pk_add_f32 v[74:75], v[74:75], v[148:149] op_sel_hi:[1,0] neg_lo:[0,1] neg_hi:[0,1]
	v_pk_add_f32 v[58:59], v[58:59], v[148:149] op_sel_hi:[1,0] neg_lo:[0,1] neg_hi:[0,1]
	v_pk_add_f32 v[76:77], v[76:77], v[148:149] op_sel_hi:[1,0] neg_lo:[0,1] neg_hi:[0,1]
	v_pk_add_f32 v[60:61], v[60:61], v[148:149] op_sel_hi:[1,0] neg_lo:[0,1] neg_hi:[0,1]
	v_pk_add_f32 v[78:79], v[78:79], v[148:149] op_sel_hi:[1,0] neg_lo:[0,1] neg_hi:[0,1]
	v_pk_add_f32 v[62:63], v[62:63], v[148:149] op_sel_hi:[1,0] neg_lo:[0,1] neg_hi:[0,1]
	v_pk_mul_f32 v[30:31], v[30:31], v[160:161] op_sel_hi:[1,0]
	v_pk_mul_f32 v[28:29], v[28:29], v[160:161] op_sel_hi:[1,0]
	v_pk_mul_f32 v[26:27], v[26:27], v[160:161] op_sel_hi:[1,0]
	v_pk_mul_f32 v[24:25], v[24:25], v[160:161] op_sel_hi:[1,0]
	v_pk_mul_f32 v[22:23], v[22:23], v[160:161] op_sel_hi:[1,0]
	v_pk_mul_f32 v[20:21], v[20:21], v[160:161] op_sel_hi:[1,0]
	v_pk_mul_f32 v[18:19], v[18:19], v[160:161] op_sel_hi:[1,0]
	v_pk_mul_f32 v[16:17], v[16:17], v[160:161] op_sel_hi:[1,0]
	v_pk_mul_f32 v[14:15], v[14:15], v[160:161] op_sel_hi:[1,0]
	v_pk_mul_f32 v[12:13], v[12:13], v[160:161] op_sel_hi:[1,0]
	v_pk_mul_f32 v[10:11], v[10:11], v[160:161] op_sel_hi:[1,0]
	v_pk_mul_f32 v[8:9], v[8:9], v[160:161] op_sel_hi:[1,0]
	v_pk_mul_f32 v[6:7], v[6:7], v[160:161] op_sel_hi:[1,0]
	v_pk_mul_f32 v[4:5], v[4:5], v[160:161] op_sel_hi:[1,0]
	v_pk_mul_f32 v[2:3], v[2:3], v[160:161] op_sel_hi:[1,0]
	v_pk_mul_f32 v[0:1], v[0:1], v[160:161] op_sel_hi:[1,0]
	v_pk_mul_f32 v[152:153], v[152:153], v[160:161] op_sel_hi:[1,0]
	v_pk_mul_f32 v[150:151], v[150:151], v[160:161] op_sel_hi:[1,0]
; #define AT_QK_LD0(kb_) do { if constexpr (NEGM) { const LAS unsigned char* kbp_ = Kl + (kb_) * KBUF + r32 * KROWB + hi * 16; AT_KLD2(0); __builtin_amdgcn_sched_barrier(0); } } while (0)
; template <int DQK, int DV, int RH, bool NEGM> ...
;     ...
;     const int NT = nkv / 64;
;     AT_GLOAD(0); AT_LSTORE(0, 0); __syncthreads();
;     int vs_prev = 2, vs_cur = 0, vs_next = 1;
;     if (!grpB) {
;         for (int t = 0; t < NT; ++t) {
;             const int kb = t & 1;
;             if (t + 1 < NT) AT_GLOAD(t + 1);
;             f32x16 p[RH][2];
;             AT_QK_LD0(kb); AT_QK(kb); AT_VLOAD(vs_cur); AT_SOFTMAX(); AT_PV(vs_cur);
;             if (t + 1 < NT) AT_LSTORE(kb ^ 1, vs_next);
;             __syncthreads();
;             vs_prev = vs_cur; vs_cur = vs_next; vs_next = (vs_next == 2) ? 0 : vs_next + 1;
.Lmla_norescale_5:
	v_exp_f32_e32 v160, v64
	v_exp_f32_e32 v161, v65
	v_exp_f32_e32 v64, v66
	v_exp_f32_e32 v65, v67
	v_exp_f32_e32 v68, v68
	v_exp_f32_e32 v69, v69
	v_exp_f32_e32 v66, v70
	v_exp_f32_e32 v67, v71
	v_cvt_pk_bf16_f32 v176, v160, v161
	v_cvt_pk_bf16_f32 v177, v64, v65
	v_cvt_pk_bf16_f32 v178, v68, v69
	v_cvt_pk_bf16_f32 v179, v66, v67
	v_exp_f32_e32 v70, v74
	v_exp_f32_e32 v71, v75
	s_waitcnt lgkmcnt(0)
	v_mfma_f32_32x32x16_bf16 v[16:31], v[136:139], v[176:179], v[16:31]
	v_exp_f32_e32 v136, v72
	v_exp_f32_e32 v137, v73
	v_exp_f32_e32 v74, v76
	v_exp_f32_e32 v75, v77
	v_exp_f32_e32 v72, v78
	v_exp_f32_e32 v73, v79
	v_exp_f32_e32 v76, v48
	v_mfma_f32_32x32x16_bf16 v[0:15], v[144:147], v[176:179], v[0:15]
	v_cvt_pk_bf16_f32 v144, v136, v137
	v_cvt_pk_bf16_f32 v145, v70, v71
	v_cvt_pk_bf16_f32 v146, v74, v75
	v_cvt_pk_bf16_f32 v147, v72, v73
	v_exp_f32_e32 v77, v49
	v_exp_f32_e32 v48, v50
	v_exp_f32_e32 v49, v51
	v_mfma_f32_32x32x16_bf16 v[16:31], v[124:127], v[144:147], v[16:31]
	v_exp_f32_e32 v52, v52
	v_exp_f32_e32 v53, v53
	v_exp_f32_e32 v50, v54
	v_exp_f32_e32 v51, v55
	v_cvt_pk_bf16_f32 v124, v76, v77
	v_cvt_pk_bf16_f32 v125, v48, v49
	v_cvt_pk_bf16_f32 v126, v52, v53
	v_mfma_f32_32x32x16_bf16 v[0:15], v[140:143], v[144:147], v[0:15]
	v_cvt_pk_bf16_f32 v127, v50, v51
	v_exp_f32_e32 v78, v56
	v_exp_f32_e32 v79, v57
	v_exp_f32_e32 v54, v58
	v_exp_f32_e32 v55, v59
	v_exp_f32_e32 v58, v60
	v_exp_f32_e32 v59, v61
	v_mfma_f32_32x32x16_bf16 v[16:31], v[132:135], v[124:127], v[16:31]
	v_exp_f32_e32 v56, v62
	v_exp_f32_e32 v57, v63
	v_cvt_pk_bf16_f32 v60, v78, v79
	v_cvt_pk_bf16_f32 v61, v54, v55
	v_cvt_pk_bf16_f32 v62, v58, v59
	v_cvt_pk_bf16_f32 v63, v56, v57
	v_mfma_f32_32x32x16_bf16 v[0:15], v[128:131], v[124:127], v[0:15]
	v_mfma_f32_32x32x16_bf16 v[16:31], v[120:123], v[60:63], v[16:31]
	v_mfma_f32_32x32x16_bf16 v[0:15], v[116:119], v[60:63], v[0:15]
	s_waitcnt vmcnt(1)
	ds_write_b128 v244, v[104:107]
	s_mov_b64 exec, s[8:9]
	ds_write_b128 v245, v[108:111]
	s_mov_b64 exec, -1
	s_waitcnt vmcnt(0)
	ds_write2_b64 v243, v[112:113], v[114:115] offset1:2
	v_pk_add_f32 v[48:49], v[64:65], v[48:49]
	v_pk_add_f32 v[60:61], v[160:161], v[76:77]
	v_pk_add_f32 v[48:49], v[152:153], v[48:49]
	v_pk_add_f32 v[50:51], v[66:67], v[50:51]
	v_pk_add_f32 v[60:61], v[150:151], v[60:61]
	v_pk_add_f32 v[52:53], v[68:69], v[52:53]
	v_pk_add_f32 v[48:49], v[50:51], v[48:49]
	v_pk_add_f32 v[50:51], v[70:71], v[54:55]
	v_pk_add_f32 v[52:53], v[52:53], v[60:61]
	v_pk_add_f32 v[60:61], v[136:137], v[78:79]
	v_pk_add_f32 v[48:49], v[50:51], v[48:49]
	v_pk_add_f32 v[50:51], v[72:73], v[56:57]
	v_pk_add_f32 v[52:53], v[60:61], v[52:53]
	v_pk_add_f32 v[58:59], v[74:75], v[58:59]
	v_pk_add_f32 v[152:153], v[50:51], v[48:49]
	v_pk_add_f32 v[150:151], v[58:59], v[52:53]
	s_waitcnt lgkmcnt(0)
	s_barrier
	global_load_dwordx4 v[104:107], v154, s[98:99]
	s_mov_b64 exec, s[8:9]
	global_load_dwordx4 v[108:111], v156, s[98:99]
	s_mov_b64 exec, -1
	global_load_dwordx4 v[112:115], v158, s[100:101]
	s_add_u32 s98, s98, 0x18000
	s_addc_u32 s99, s99, 0
	s_add_u32 s100, s100, 0x80
	s_addc_u32 s101, s101, 0
	ds_read_b128 v[48:51], v169
	ds_read_b128 v[52:55], v169 offset:32
	ds_read_b128 v[116:119], v169 offset:6656
	ds_read_b128 v[120:123], v169 offset:6688
	s_waitcnt lgkmcnt(3)
	v_mfma_f32_32x32x16_bf16 v[64:79], v[48:51], v[100:103], v[32:47]
	ds_read_b128 v[124:127], v169 offset:64
	ds_read_b128 v[128:131], v169 offset:96
	ds_read_b128 v[132:135], v169 offset:6720
	ds_read_b128 v[136:139], v169 offset:6752
	s_waitcnt lgkmcnt(4)
	v_mfma_f32_32x32x16_bf16 v[64:79], v[52:55], v[96:99], v[64:79]
	v_mfma_f32_32x32x16_bf16 v[48:63], v[116:119], v[100:103], v[32:47]
	v_mfma_f32_32x32x16_bf16 v[48:63], v[120:123], v[96:99], v[48:63]
	s_waitcnt lgkmcnt(1)
	v_mfma_f32_32x32x16_bf16 v[64:79], v[124:127], v[92:95], v[64:79]
	v_mfma_f32_32x32x16_bf16 v[48:63], v[132:135], v[92:95], v[48:63]
	v_mfma_f32_32x32x16_bf16 v[64:79], v[128:131], v[88:91], v[64:79]
	ds_read_b128 v[116:119], v169 offset:128
	ds_read_b128 v[120:123], v169 offset:160
	ds_read_b128 v[128:131], v169 offset:6784
	ds_read_b128 v[176:179], v169 offset:6816
	s_waitcnt lgkmcnt(3)
	v_mfma_f32_32x32x16_bf16 v[48:63], v[136:139], v[88:91], v[48:63]
	v_mfma_f32_32x32x16_bf16 v[64:79], v[116:119], v[84:87], v[64:79]
	ds_read_b128 v[136:139], v170 offset:26624
	ds_read_b128 v[124:127], v170 offset:26656
	s_waitcnt lgkmcnt(3)
	v_mfma_f32_32x32x16_bf16 v[48:63], v[128:131], v[84:87], v[48:63]
	v_mfma_f32_32x32x16_bf16 v[64:79], v[120:123], v[80:83], v[64:79]
	ds_read_b128 v[132:135], v170 offset:26688
	ds_read_b128 v[120:123], v170 offset:26720
	ds_read_b128 v[144:147], v170 offset:31232
	ds_read_b128 v[140:143], v170 offset:31264
	ds_read_b128 v[128:131], v170 offset:31296
	ds_read_b128 v[116:119], v170 offset:31328
	s_waitcnt lgkmcnt(8)
	v_mfma_f32_32x32x16_bf16 v[48:63], v[176:179], v[80:83], v[48:63]
	s_add_i32 s43, s43, 1
	s_nop 10
	v_max_f32_e32 v148, v64, v48
	v_max_f32_e32 v160, v65, v49
	v_max_f32_e32 v161, v67, v51
	v_max3_f32 v176, v66, v50, v70
	v_max3_f32 v161, v161, v71, v55
	v_max3_f32 v148, v148, v68, v52
	v_max3_f32 v160, v160, v69, v53
	v_max3_f32 v176, v176, v54, v74
	v_max3_f32 v161, v161, v75, v59
	v_max3_f32 v148, v148, v72, v56
	v_max3_f32 v160, v160, v73, v57
	v_max3_f32 v176, v176, v58, v78
	v_max3_f32 v161, v161, v79, v63
	v_max3_f32 v148, v148, v76, v60
	v_max3_f32 v160, v160, v77, v61
	v_max3_f32 v161, v176, v62, v161
	v_max3_f32 v148, v148, v160, v161
	v_cmp_lt_f32_e32 vcc, s59, v148
	s_cbranch_vccz .Lmla_norescale_0
	v_mov_b32_e32 v160, v148
	s_nop 1
	v_permlane32_swap_b32_e32 v148, v160
	v_max_f32_e32 v148, v148, v160
	v_max_f32_e32 v32, v148, v148
	v_max_f32_e32 v148, 0, v32
	v_exp_f32_e64 v160, -v148
	v_add_f32_e32 v168, v168, v148
	v_xor_b32_e32 v32, 0x80000000, v168
	v_mov_b32_e32 v33, v32
	v_mov_b32_e32 v34, v32
	v_mov_b32_e32 v35, v32
	v_mov_b32_e32 v36, v32
	v_mov_b32_e32 v37, v32
	v_mov_b32_e32 v38, v32
	v_mov_b32_e32 v39, v32
	v_mov_b32_e32 v40, v32
	v_mov_b32_e32 v41, v32
	v_mov_b32_e32 v42, v32
	v_mov_b32_e32 v43, v32
	v_mov_b32_e32 v44, v32
	v_mov_b32_e32 v45, v32
	v_mov_b32_e32 v46, v32
	v_mov_b32_e32 v47, v32
	v_pk_add_f32 v[64:65], v[64:65], v[148:149] op_sel_hi:[1,0] neg_lo:[0,1] neg_hi:[0,1]
	v_pk_add_f32 v[48:49], v[48:49], v[148:149] op_sel_hi:[1,0] neg_lo:[0,1] neg_hi:[0,1]
	v_pk_add_f32 v[66:67], v[66:67], v[148:149] op_sel_hi:[1,0] neg_lo:[0,1] neg_hi:[0,1]
	v_pk_add_f32 v[50:51], v[50:51], v[148:149] op_sel_hi:[1,0] neg_lo:[0,1] neg_hi:[0,1]
	v_pk_add_f32 v[68:69], v[68:69], v[148:149] op_sel_hi:[1,0] neg_lo:[0,1] neg_hi:[0,1]
	v_pk_add_f32 v[52:53], v[52:53], v[148:149] op_sel_hi:[1,0] neg_lo:[0,1] neg_hi:[0,1]
	v_pk_add_f32 v[70:71], v[70:71], v[148:149] op_sel_hi:[1,0] neg_lo:[0,1] neg_hi:[0,1]
	v_pk_add_f32 v[54:55], v[54:55], v[148:149] op_sel_hi:[1,0] neg_lo:[0,1] neg_hi:[0,1]
	v_pk_add_f32 v[72:73], v[72:73], v[148:149] op_sel_hi:[1,0] neg_lo:[0,1] neg_hi:[0,1]
	v_pk_add_f32 v[56:57], v[56:57], v[148:149] op_sel_hi:[1,0] neg_lo:[0,1] neg_hi:[0,1]
	v_pk_add_f32 v[74:75], v[74:75], v[148:149] op_sel_hi:[1,0] neg_lo:[0,1] neg_hi:[0,1]
	v_pk_add_f32 v[58:59], v[58:59], v[148:149] op_sel_hi:[1,0] neg_lo:[0,1] neg_hi:[0,1]
	v_pk_add_f32 v[76:77], v[76:77], v[148:149] op_sel_hi:[1,0] neg_lo:[0,1] neg_hi:[0,1]
	v_pk_add_f32 v[60:61], v[60:61], v[148:149] op_sel_hi:[1,0] neg_lo:[0,1] neg_hi:[0,1]
	v_pk_add_f32 v[78:79], v[78:79], v[148:149] op_sel_hi:[1,0] neg_lo:[0,1] neg_hi:[0,1]
	v_pk_add_f32 v[62:63], v[62:63], v[148:149] op_sel_hi:[1,0] neg_lo:[0,1] neg_hi:[0,1]
	v_pk_mul_f32 v[30:31], v[30:31], v[160:161] op_sel_hi:[1,0]
	v_pk_mul_f32 v[28:29], v[28:29], v[160:161] op_sel_hi:[1,0]
	v_pk_mul_f32 v[26:27], v[26:27], v[160:161] op_sel_hi:[1,0]
	v_pk_mul_f32 v[24:25], v[24:25], v[160:161] op_sel_hi:[1,0]
	v_pk_mul_f32 v[22:23], v[22:23], v[160:161] op_sel_hi:[1,0]
	v_pk_mul_f32 v[20:21], v[20:21], v[160:161] op_sel_hi:[1,0]
	v_pk_mul_f32 v[18:19], v[18:19], v[160:161] op_sel_hi:[1,0]
	v_pk_mul_f32 v[16:17], v[16:17], v[160:161] op_sel_hi:[1,0]
	v_pk_mul_f32 v[14:15], v[14:15], v[160:161] op_sel_hi:[1,0]
	v_pk_mul_f32 v[12:13], v[12:13], v[160:161] op_sel_hi:[1,0]
	v_pk_mul_f32 v[10:11], v[10:11], v[160:161] op_sel_hi:[1,0]
	v_pk_mul_f32 v[8:9], v[8:9], v[160:161] op_sel_hi:[1,0]
	v_pk_mul_f32 v[6:7], v[6:7], v[160:161] op_sel_hi:[1,0]
	v_pk_mul_f32 v[4:5], v[4:5], v[160:161] op_sel_hi:[1,0]
	v_pk_mul_f32 v[2:3], v[2:3], v[160:161] op_sel_hi:[1,0]
	v_pk_mul_f32 v[0:1], v[0:1], v[160:161] op_sel_hi:[1,0]
	v_pk_mul_f32 v[152:153], v[152:153], v[160:161] op_sel_hi:[1,0]
	v_pk_mul_f32 v[150:151], v[150:151], v[160:161] op_sel_hi:[1,0]
; #define AT_QK_LD0(kb_) do { if constexpr (NEGM) { const LAS unsigned char* kbp_ = Kl + (kb_) * KBUF + r32 * KROWB + hi * 16; AT_KLD2(0); __builtin_amdgcn_sched_barrier(0); } } while (0)
; template <int DQK, int DV, int RH, bool NEGM> ...
;     ...
;     const int NT = nkv / 64;
;     AT_GLOAD(0); AT_LSTORE(0, 0); __syncthreads();
;     int vs_prev = 2, vs_cur = 0, vs_next = 1;
;     if (!grpB) {
;         for (int t = 0; t < NT; ++t) {
;             const int kb = t & 1;
;             if (t + 1 < NT) AT_GLOAD(t + 1);
;             f32x16 p[RH][2];
;             AT_QK_LD0(kb); AT_QK(kb); AT_VLOAD(vs_cur); AT_SOFTMAX(); AT_PV(vs_cur);
;             if (t + 1 < NT) AT_LSTORE(kb ^ 1, vs_next);
;             __syncthreads();
;             vs_prev = vs_cur; vs_cur = vs_next; vs_next = (vs_next == 2) ? 0 : vs_next + 1;
.Lmla_norescale_0:
	v_exp_f32_e32 v160, v64
	v_exp_f32_e32 v161, v65
	v_exp_f32_e32 v64, v66
	v_exp_f32_e32 v65, v67
	v_exp_f32_e32 v68, v68
	v_exp_f32_e32 v69, v69
	v_exp_f32_e32 v66, v70
	v_exp_f32_e32 v67, v71
	v_cvt_pk_bf16_f32 v176, v160, v161
	v_cvt_pk_bf16_f32 v177, v64, v65
	v_cvt_pk_bf16_f32 v178, v68, v69
	v_cvt_pk_bf16_f32 v179, v66, v67
	v_exp_f32_e32 v70, v74
	v_exp_f32_e32 v71, v75
	s_waitcnt lgkmcnt(0)
	v_mfma_f32_32x32x16_bf16 v[16:31], v[136:139], v[176:179], v[16:31]
	v_exp_f32_e32 v136, v72
	v_exp_f32_e32 v137, v73
	v_exp_f32_e32 v74, v76
	v_exp_f32_e32 v75, v77
	v_exp_f32_e32 v72, v78
	v_exp_f32_e32 v73, v79
	v_exp_f32_e32 v76, v48
	v_mfma_f32_32x32x16_bf16 v[0:15], v[144:147], v[176:179], v[0:15]
	v_cvt_pk_bf16_f32 v144, v136, v137
	v_cvt_pk_bf16_f32 v145, v70, v71
	v_cvt_pk_bf16_f32 v146, v74, v75
	v_cvt_pk_bf16_f32 v147, v72, v73
	v_exp_f32_e32 v77, v49
	v_exp_f32_e32 v48, v50
	v_exp_f32_e32 v49, v51
	v_mfma_f32_32x32x16_bf16 v[16:31], v[124:127], v[144:147], v[16:31]
	v_exp_f32_e32 v52, v52
	v_exp_f32_e32 v53, v53
	v_exp_f32_e32 v50, v54
	v_exp_f32_e32 v51, v55
	v_cvt_pk_bf16_f32 v124, v76, v77
	v_cvt_pk_bf16_f32 v125, v48, v49
	v_cvt_pk_bf16_f32 v126, v52, v53
	v_mfma_f32_32x32x16_bf16 v[0:15], v[140:143], v[144:147], v[0:15]
	v_cvt_pk_bf16_f32 v127, v50, v51
	v_exp_f32_e32 v78, v56
	v_exp_f32_e32 v79, v57
	v_exp_f32_e32 v54, v58
	v_exp_f32_e32 v55, v59
	v_exp_f32_e32 v58, v60
	v_exp_f32_e32 v59, v61
	v_mfma_f32_32x32x16_bf16 v[16:31], v[132:135], v[124:127], v[16:31]
	v_exp_f32_e32 v56, v62
	v_exp_f32_e32 v57, v63
	v_cvt_pk_bf16_f32 v60, v78, v79
	v_cvt_pk_bf16_f32 v61, v54, v55
	v_cvt_pk_bf16_f32 v62, v58, v59
	v_cvt_pk_bf16_f32 v63, v56, v57
	v_mfma_f32_32x32x16_bf16 v[0:15], v[128:131], v[124:127], v[0:15]
	v_mfma_f32_32x32x16_bf16 v[16:31], v[120:123], v[60:63], v[16:31]
	v_mfma_f32_32x32x16_bf16 v[0:15], v[116:119], v[60:63], v[0:15]
	s_waitcnt vmcnt(1)
	ds_write_b128 v244, v[104:107] offset:13312
	s_mov_b64 exec, s[8:9]
	ds_write_b128 v245, v[108:111] offset:13312
	s_mov_b64 exec, -1
	s_waitcnt vmcnt(0)
	ds_write2_b64 v246, v[112:113], v[114:115] offset1:2
	v_pk_add_f32 v[48:49], v[64:65], v[48:49]
	v_pk_add_f32 v[60:61], v[160:161], v[76:77]
	v_pk_add_f32 v[48:49], v[152:153], v[48:49]
	v_pk_add_f32 v[50:51], v[66:67], v[50:51]
	v_pk_add_f32 v[60:61], v[150:151], v[60:61]
	v_pk_add_f32 v[52:53], v[68:69], v[52:53]
	v_pk_add_f32 v[48:49], v[50:51], v[48:49]
	v_pk_add_f32 v[50:51], v[70:71], v[54:55]
	v_pk_add_f32 v[52:53], v[52:53], v[60:61]
	v_pk_add_f32 v[60:61], v[136:137], v[78:79]
	v_pk_add_f32 v[48:49], v[50:51], v[48:49]
	v_pk_add_f32 v[50:51], v[72:73], v[56:57]
	v_pk_add_f32 v[52:53], v[60:61], v[52:53]
	v_pk_add_f32 v[58:59], v[74:75], v[58:59]
	v_pk_add_f32 v[152:153], v[50:51], v[48:49]
	v_pk_add_f32 v[150:151], v[58:59], v[52:53]
	s_waitcnt lgkmcnt(0)
	s_barrier
	s_branch .Lmla_loop
.Lmla_exit:
	s_mov_b32 s21, 0
	ds_read_b128 v[64:67], v169 offset:13312
	ds_read_b128 v[68:71], v169 offset:13344
	ds_read_b128 v[72:75], v169 offset:19968
	ds_read_b128 v[76:79], v169 offset:20000
	s_waitcnt lgkmcnt(3)
	v_mfma_f32_32x32x16_bf16 v[48:63], v[64:67], v[100:103], v[32:47]
	ds_read_b128 v[64:67], v169 offset:13376
	ds_read_b128 v[104:107], v169 offset:13408
	ds_read_b128 v[108:111], v169 offset:20032
	ds_read_b128 v[112:115], v169 offset:20064
	s_waitcnt lgkmcnt(6)
	v_mfma_f32_32x32x16_bf16 v[48:63], v[68:71], v[96:99], v[48:63]
	s_waitcnt lgkmcnt(5)
	v_mfma_f32_32x32x16_bf16 v[32:47], v[72:75], v[100:103], v[32:47]
	s_waitcnt lgkmcnt(4)
	v_mfma_f32_32x32x16_bf16 v[32:47], v[76:79], v[96:99], v[32:47]
	s_waitcnt lgkmcnt(3)
	v_mfma_f32_32x32x16_bf16 v[48:63], v[64:67], v[92:95], v[48:63]
	ds_read_b128 v[64:67], v169 offset:13440
	ds_read_b128 v[68:71], v169 offset:13472
	ds_read_b128 v[72:75], v169 offset:20096
	ds_read_b128 v[76:79], v169 offset:20128
	s_waitcnt lgkmcnt(5)
	v_mfma_f32_32x32x16_bf16 v[32:47], v[108:111], v[92:95], v[32:47]
	v_mfma_f32_32x32x16_bf16 v[48:63], v[104:107], v[88:91], v[48:63]
	s_waitcnt lgkmcnt(4)
	v_mfma_f32_32x32x16_bf16 v[32:47], v[112:115], v[88:91], v[32:47]
	s_waitcnt lgkmcnt(3)
	v_mfma_f32_32x32x16_bf16 v[48:63], v[64:67], v[84:87], v[48:63]
	v_add3_u32 v64, v167, s21, v173
	v_add_u32_e32 v65, 0x6800, v64
	ds_read_b128 v[108:111], v65
	ds_read_b128 v[104:107], v65 offset:32
	ds_read_b128 v[96:99], v65 offset:64
	ds_read_b128 v[88:91], v65 offset:96
	s_waitcnt lgkmcnt(5)
	v_mfma_f32_32x32x16_bf16 v[32:47], v[72:75], v[84:87], v[32:47]
	ds_read_b128 v[112:115], v65 offset:4608
	ds_read_b128 v[100:103], v65 offset:4640
	ds_read_b128 v[92:95], v65 offset:4672
	ds_read_b128 v[84:87], v65 offset:4704
	v_mfma_f32_32x32x16_bf16 v[48:63], v[68:71], v[80:83], v[48:63]
	s_waitcnt lgkmcnt(8)
	v_mfma_f32_32x32x16_bf16 v[32:47], v[76:79], v[80:83], v[32:47]
	s_nop 11
	v_max_f32_e32 v64, v32, v32
	v_max_f32_e32 v65, v48, v48
	v_max_f32_e32 v64, v65, v64
	v_max_f32_e32 v65, v33, v33
	v_max_f32_e32 v66, v49, v49
	v_max_f32_e32 v65, v66, v65
	v_max_f32_e32 v66, v35, v35
	v_max_f32_e32 v67, v51, v51
	v_max_f32_e32 v66, v67, v66
	v_max3_f32 v67, v50, v34, v54
	v_max3_f32 v66, v66, v55, v39
	v_max3_f32 v64, v64, v52, v36
	v_max3_f32 v65, v65, v53, v37
	v_max3_f32 v67, v67, v38, v58
	v_max3_f32 v66, v66, v59, v43
	v_max3_f32 v64, v64, v56, v40
	v_max3_f32 v65, v65, v57, v41
	v_max3_f32 v67, v67, v42, v62
	v_max3_f32 v66, v66, v63, v47
	v_max3_f32 v64, v64, v60, v44
	v_max3_f32 v65, v65, v61, v45
	v_max3_f32 v66, v67, v46, v66
	v_max3_f32 v64, v64, v65, v66
	v_mov_b32_e32 v65, v64
	s_nop 1
	v_permlane32_swap_b32_e32 v64, v65
	v_max_f32_e32 v65, v65, v65
	v_max_f32_e32 v64, v64, v64
	v_max_f32_e32 v64, v64, v65
	v_cmp_lt_f32_e32 vcc, s59, v64
	s_cbranch_vccnz .LBB0_861
	v_mov_b32_e32 v64, v151
	v_mov_b32_e32 v151, v152
	v_mov_b32_e32 v65, v153
	s_branch .LBB0_862

; __global__ void __launch_bounds__(512, 2) fwd_mega(Args a) {
	.amdhsa_kernel _Z8fwd_mega4Args
		.amdhsa_group_segment_fixed_size 0
		.amdhsa_private_segment_fixed_size 0
		.amdhsa_kernarg_size 496
		.amdhsa_user_sgpr_count 2
		.amdhsa_user_sgpr_dispatch_ptr 0
		.amdhsa_user_sgpr_queue_ptr 0
		.amdhsa_user_sgpr_kernarg_segment_ptr 1
		.amdhsa_user_sgpr_dispatch_id 0
		.amdhsa_user_sgpr_kernarg_preload_length 0
		.amdhsa_user_sgpr_kernarg_preload_offset 0
		.amdhsa_user_sgpr_private_segment_size 0
		.amdhsa_uses_dynamic_stack 0
		.amdhsa_enable_private_segment 0
		.amdhsa_system_sgpr_workgroup_id_x 1
		.amdhsa_system_sgpr_workgroup_id_y 0
		.amdhsa_system_sgpr_workgroup_id_z 0
		.amdhsa_system_sgpr_workgroup_info 0
		.amdhsa_system_vgpr_workitem_id 2
		.amdhsa_next_free_vgpr 248
		.amdhsa_next_free_sgpr 102
		.amdhsa_accum_offset 248
		.amdhsa_reserve_vcc 1
		.amdhsa_float_round_mode_32 0
		.amdhsa_float_round_mode_16_64 0
		.amdhsa_float_denorm_mode_32 3
		.amdhsa_float_denorm_mode_16_64 3
		.amdhsa_dx10_clamp 1
		.amdhsa_ieee_mode 1
		.amdhsa_fp16_overflow 0
		.amdhsa_tg_split 0
		.amdhsa_exception_fp_ieee_invalid_op 0
		.amdhsa_exception_fp_denorm_src 0
		.amdhsa_exception_fp_ieee_div_zero 0
		.amdhsa_exception_fp_ieee_overflow 0
		.amdhsa_exception_fp_ieee_underflow 0
		.amdhsa_exception_fp_ieee_inexact 0
		.amdhsa_exception_int_div_zero 0
	.end_amdhsa_kernel

; __global__ void __launch_bounds__(512, 2) fwd_mega(Args a) {
.Lfunc_end0:
	.size	_Z8fwd_mega4Args, .Lfunc_end0-_Z8fwd_mega4Args
	.set _Z8fwd_mega4Args.num_vgpr, 248
	.set _Z8fwd_mega4Args.num_agpr, 0
	.set _Z8fwd_mega4Args.numbered_sgpr, 98
	.set _Z8fwd_mega4Args.num_named_barrier, 0
	.set _Z8fwd_mega4Args.private_seg_size, 0
	.set _Z8fwd_mega4Args.uses_vcc, 1
	.set _Z8fwd_mega4Args.uses_flat_scratch, 0
	.set _Z8fwd_mega4Args.has_dyn_sized_stack, 0
	.set _Z8fwd_mega4Args.has_recursion, 0
	.set _Z8fwd_mega4Args.has_indirect_call, 0

; __global__ void __launch_bounds__(512, 2) fwd_mega(Args a) {
amdhsa.kernels:
  - .agpr_count:     0
    .args:
      - .offset:         0
        .size:           240
        .value_kind:     by_value
      - .offset:         240
        .size:           4
        .value_kind:     hidden_block_count_x
      - .offset:         244
        .size:           4
        .value_kind:     hidden_block_count_y
      - .offset:         248
        .size:           4
        .value_kind:     hidden_block_count_z
      - .offset:         252
        .size:           2
        .value_kind:     hidden_group_size_x
      - .offset:         254
        .size:           2
        .value_kind:     hidden_group_size_y
      - .offset:         256
        .size:           2
        .value_kind:     hidden_group_size_z
      - .offset:         258
        .size:           2
        .value_kind:     hidden_remainder_x
      - .offset:         260
        .size:           2
        .value_kind:     hidden_remainder_y
      - .offset:         262
        .size:           2
        .value_kind:     hidden_remainder_z
      - .offset:         280
        .size:           8
        .value_kind:     hidden_global_offset_x
      - .offset:         288
        .size:           8
        .value_kind:     hidden_global_offset_y
      - .offset:         296
        .size:           8
        .value_kind:     hidden_global_offset_z
      - .offset:         304
        .size:           2
        .value_kind:     hidden_grid_dims
      - .offset:         328
        .size:           8
        .value_kind:     hidden_multigrid_sync_arg
      - .offset:         360
        .size:           4
        .value_kind:     hidden_dynamic_lds_size
    .group_segment_fixed_size: 0
    .kernarg_segment_align: 8
    .kernarg_segment_size: 496
    .language:       OpenCL C
    .language_version:
      - 2
      - 0
    .max_flat_workgroup_size: 512
    .name:           _Z8fwd_mega4Args
    .private_segment_fixed_size: 0
    .sgpr_count:     108
    .sgpr_spill_count: 6
    .symbol:         _Z8fwd_mega4Args.kd
    .uniform_work_group_size: 1
    .uses_dynamic_stack: false
    .vgpr_count:     248
    .vgpr_spill_count: 0
    .wavefront_size: 64
